# down-projection: own K pipeline (saddr LDS-DMA, deferred-MFMA loop) on chunk-major ACT (written by the up-projection epilogue as whole 1 KB chunks) and chunk-major W2A/W2B
# speedup vs baseline: 1.1238x; 1.0184x over previous
.LBB0_42:
	s_add_i32 s0, s50, -1
	s_mul_hi_i32 s1, s0, 0x2e8ba2e9
	s_lshr_b32 s2, s1, 31
	s_ashr_i32 s1, s1, 1
	s_add_i32 s4, s1, s2
	s_mov_b32 s2, s4
	v_writelane_b32 v214, s2, 57
	s_mul_i32 s1, s4, 11
	s_sub_i32 s21, s0, s1
	v_writelane_b32 v214, s3, 58
	s_mov_b64 s[2:3], 0
	s_mov_b64 s[0:1], -1
	s_cmp_lt_i32 s21, 5
	v_writelane_b32 v214, s2, 59
	s_nop 1
	v_writelane_b32 v214, s3, 60
	s_cbranch_scc1 .LBB0_167
	s_cmp_gt_i32 s21, 6
	s_cbranch_scc0 .LBB0_57
	v_readlane_b32 s8, v217, 20
	s_cmp_gt_i32 s21, 7
	v_readlane_b32 s9, v217, 21
	s_cbranch_scc0 .LBB0_58
	s_cmp_gt_i32 s21, 8
	s_cbranch_scc0 .LBB0_59
	s_cmp_eq_u32 s21, 9
	s_cbranch_scc0 .LBB0_71
	v_readlane_b32 s11, v217, 0
	v_readlane_b32 s12, v214, 57
	s_and_b32 s14, s11, 7
	s_lshr_b32 s15, s11, 3
	s_mul_hi_u32 s16, s12, 0x3500000
	s_mul_i32 s12, s12, 0x3500000
	s_add_u32 s40, s48, s12
	s_addc_u32 s41, s49, s16
	s_add_u32 s40, s40, 0x11a4e000
	s_addc_u32 s41, s41, 0
	v_and_b32_e32 v141, 15, v142
	v_lshrrev_b32_e32 v139, 4, v142
	v_and_b32_e32 v139, 3, v139
	v_lshlrev_b32_e32 v140, 6, v141
	v_lshl_add_u32 v140, v139, 4, v140
	v_lshrrev_b32_e32 v139, 3, v141
	v_lshlrev_b32_e32 v139, 5, v139
	v_xor_b32_e32 v135, v140, v139
	v_lshrrev_b32_e32 v139, 7, v142
	v_lshl_add_u32 v134, v139, 12, v135
	v_lshrrev_b32_e32 v139, 6, v142
	v_and_b32_e32 v139, 1, v139
	v_lshl_add_u32 v135, v139, 12, v135
	v_add_u32_e32 v135, 0x4000, v135
	v_and_b32_e32 v141, 63, v142
	v_lshrrev_b32_e32 v139, 2, v141
	v_lshrrev_b32_e32 v140, 6, v142
	v_lshlrev_b32_e32 v139, 6, v139
	v_lshl_add_u32 v139, v140, 15, v139
	v_and_b32_e32 v140, 3, v141
	v_lshlrev_b32_e32 v140, 4, v140
	v_lshrrev_b32_e32 v141, 5, v141
	v_lshlrev_b32_e32 v141, 5, v141
	v_xor_b32_e32 v140, v140, v141
	v_add_u32_e32 v136, v139, v140
	v_add_u32_e32 v137, 0x40000, v136
	v_lshrrev_b32_e32 v139, 7, v142
	v_and_b32_e32 v141, 15, v142
	v_mul_u32_u24_e32 v139, 0x58000, v139
	v_lshl_add_u32 v139, v141, 6, v139
	v_lshrrev_b32_e32 v140, 6, v142
	v_and_b32_e32 v140, 1, v140
	v_lshlrev_b32_e32 v140, 10, v140
	v_lshrrev_b32_e32 v141, 4, v142
	v_and_b32_e32 v141, 3, v141
	v_lshl_add_u32 v140, v141, 3, v140
	v_add_u32_e32 v138, v139, v140
	v_and_b32_e32 v141, 1, v141
	v_mul_u32_u24_e32 v141, 24, v141
	v_add_u32_e32 v138, v138, v141
	v_lshlrev_b32_e32 v161, 11, v142
	v_lshrrev_b32_e32 v141, 6, v142
	v_lshlrev_b32_e32 v141, 10, v141
	s_nop 0
	v_readfirstlane_b32 s6, v141
	s_mov_b32 s10, s15
.Lg2_a_item1:
	s_mul_i32 s11, s10, 0x2aab
	s_lshr_b32 s11, s11, 16
	s_mul_i32 s12, s11, 6
	s_sub_u32 s12, s10, s12
	s_mov_b32 s16, 0
	s_and_b32 s17, s14, 3
	s_mul_i32 s17, s17, 6
	s_add_u32 s12, s12, s17
	s_lshl_b32 s12, s12, 8
	s_add_u32 s12, s12, s16
	s_lshr_b32 s17, s14, 2
	s_mul_i32 s17, s17, 22
	s_lshl_b32 s11, s11, 1
	s_add_u32 s11, s11, s17
	s_lshl_b32 s16, s12, 11
	s_add_u32 s0, s24, s16
	s_addc_u32 s1, s25, 0
	s_lshl_b32 s16, s11, 18
	s_add_u32 s2, s40, s16
	s_addc_u32 s3, s41, 0
	s_mul_i32 s16, s12, 0x1600
	s_lshl_b32 s17, s11, 11
	s_add_u32 s16, s16, s17
	s_add_u32 s4, s26, s16
	s_addc_u32 s5, s27, 0
	s_add_u32 m0, s6, 0x0
	s_nop 0
	global_load_lds_dwordx4 v136, s[0:1]
	s_add_u32 m0, s6, 0x2000
	s_nop 0
	global_load_lds_dwordx4 v137, s[0:1]
	s_add_u32 m0, s6, 0x4000
	s_nop 0
	global_load_lds_dwordx4 v136, s[2:3]
	s_add_u32 m0, s6, 0x6000
	s_nop 0
	global_load_lds_dwordx4 v137, s[2:3]
	s_add_u32 s0, s0, 1024
	s_addc_u32 s1, s1, 0
	s_add_u32 s2, s2, 1024
	s_addc_u32 s3, s3, 0
	s_add_u32 m0, s6, 0x8000
	s_nop 0
	global_load_lds_dwordx4 v136, s[0:1]
	s_add_u32 m0, s6, 0xa000
	s_nop 0
	global_load_lds_dwordx4 v137, s[0:1]
	s_add_u32 m0, s6, 0xc000
	s_nop 0
	global_load_lds_dwordx4 v136, s[2:3]
	s_add_u32 m0, s6, 0xe000
	s_nop 0
	global_load_lds_dwordx4 v137, s[2:3]
	s_add_u32 s0, s0, 1024
	s_addc_u32 s1, s1, 0
	s_add_u32 s2, s2, 1024
	s_addc_u32 s3, s3, 0
	s_add_u32 m0, s6, 0x10000
	s_nop 0
	global_load_lds_dwordx4 v136, s[0:1]
	s_add_u32 m0, s6, 0x12000
	s_nop 0
	global_load_lds_dwordx4 v137, s[0:1]
	s_add_u32 m0, s6, 0x14000
	s_nop 0
	global_load_lds_dwordx4 v136, s[2:3]
	s_add_u32 m0, s6, 0x16000
	s_nop 0
	global_load_lds_dwordx4 v137, s[2:3]
	s_add_u32 s0, s0, 1024
	s_addc_u32 s1, s1, 0
	s_add_u32 s2, s2, 1024
	s_addc_u32 s3, s3, 0
	v_mov_b32_e32 v2, 0
	v_mov_b32_e32 v3, 0
	v_mov_b32_e32 v4, 0
	v_mov_b32_e32 v5, 0
	v_mov_b32_e32 v6, 0
	v_mov_b32_e32 v7, 0
	v_mov_b32_e32 v8, 0
	v_mov_b32_e32 v9, 0
	v_mov_b32_e32 v10, 0
	v_mov_b32_e32 v11, 0
	v_mov_b32_e32 v12, 0
	v_mov_b32_e32 v13, 0
	v_mov_b32_e32 v14, 0
	v_mov_b32_e32 v15, 0
	v_mov_b32_e32 v16, 0
	v_mov_b32_e32 v17, 0
	v_mov_b32_e32 v18, 0
	v_mov_b32_e32 v19, 0
	v_mov_b32_e32 v20, 0
	v_mov_b32_e32 v21, 0
	v_mov_b32_e32 v22, 0
	v_mov_b32_e32 v23, 0
	v_mov_b32_e32 v24, 0
	v_mov_b32_e32 v25, 0
	v_mov_b32_e32 v26, 0
	v_mov_b32_e32 v27, 0
	v_mov_b32_e32 v28, 0
	v_mov_b32_e32 v29, 0
	v_mov_b32_e32 v30, 0
	v_mov_b32_e32 v31, 0
	v_mov_b32_e32 v32, 0
	v_mov_b32_e32 v33, 0
	v_mov_b32_e32 v34, 0
	v_mov_b32_e32 v35, 0
	v_mov_b32_e32 v36, 0
	v_mov_b32_e32 v37, 0
	v_mov_b32_e32 v38, 0
	v_mov_b32_e32 v39, 0
	v_mov_b32_e32 v40, 0
	v_mov_b32_e32 v41, 0
	v_mov_b32_e32 v42, 0
	v_mov_b32_e32 v43, 0
	v_mov_b32_e32 v44, 0
	v_mov_b32_e32 v45, 0
	v_mov_b32_e32 v46, 0
	v_mov_b32_e32 v47, 0
	v_mov_b32_e32 v48, 0
	v_mov_b32_e32 v49, 0
	v_mov_b32_e32 v50, 0
	v_mov_b32_e32 v51, 0
	v_mov_b32_e32 v52, 0
	v_mov_b32_e32 v53, 0
	v_mov_b32_e32 v54, 0
	v_mov_b32_e32 v55, 0
	v_mov_b32_e32 v56, 0
	v_mov_b32_e32 v57, 0
	v_mov_b32_e32 v58, 0
	v_mov_b32_e32 v59, 0
	v_mov_b32_e32 v60, 0
	v_mov_b32_e32 v61, 0
	v_mov_b32_e32 v62, 0
	v_mov_b32_e32 v63, 0
	v_mov_b32_e32 v64, 0
	v_mov_b32_e32 v65, 0
	v_mov_b32_e32 v66, 0
	v_mov_b32_e32 v67, 0
	v_mov_b32_e32 v68, 0
	v_mov_b32_e32 v69, 0
	v_mov_b32_e32 v70, 0
	v_mov_b32_e32 v71, 0
	v_mov_b32_e32 v72, 0
	v_mov_b32_e32 v73, 0
	v_mov_b32_e32 v74, 0
	v_mov_b32_e32 v75, 0
	v_mov_b32_e32 v76, 0
	v_mov_b32_e32 v77, 0
	v_mov_b32_e32 v78, 0
	v_mov_b32_e32 v79, 0
	v_mov_b32_e32 v80, 0
	v_mov_b32_e32 v81, 0
	v_mov_b32_e32 v82, 0
	v_mov_b32_e32 v83, 0
	v_mov_b32_e32 v84, 0
	v_mov_b32_e32 v85, 0
	v_mov_b32_e32 v86, 0
	v_mov_b32_e32 v87, 0
	v_mov_b32_e32 v88, 0
	v_mov_b32_e32 v89, 0
	v_mov_b32_e32 v90, 0
	v_mov_b32_e32 v91, 0
	v_mov_b32_e32 v92, 0
	v_mov_b32_e32 v93, 0
	v_mov_b32_e32 v94, 0
	v_mov_b32_e32 v95, 0
	v_mov_b32_e32 v96, 0
	v_mov_b32_e32 v97, 0
	v_mov_b32_e32 v98, 0
	v_mov_b32_e32 v99, 0
	v_mov_b32_e32 v100, 0
	v_mov_b32_e32 v101, 0
	v_mov_b32_e32 v102, 0
	v_mov_b32_e32 v103, 0
	v_mov_b32_e32 v104, 0
	v_mov_b32_e32 v105, 0
	v_mov_b32_e32 v106, 0
	v_mov_b32_e32 v107, 0
	v_mov_b32_e32 v108, 0
	v_mov_b32_e32 v109, 0
	v_mov_b32_e32 v110, 0
	v_mov_b32_e32 v111, 0
	v_mov_b32_e32 v112, 0
	v_mov_b32_e32 v113, 0
	v_mov_b32_e32 v114, 0
	v_mov_b32_e32 v115, 0
	v_mov_b32_e32 v116, 0
	v_mov_b32_e32 v117, 0
	v_mov_b32_e32 v118, 0
	v_mov_b32_e32 v119, 0
	v_mov_b32_e32 v120, 0
	v_mov_b32_e32 v121, 0
	v_mov_b32_e32 v122, 0
	v_mov_b32_e32 v123, 0
	v_mov_b32_e32 v124, 0
	v_mov_b32_e32 v125, 0
	v_mov_b32_e32 v126, 0
	v_mov_b32_e32 v127, 0
	v_mov_b32_e32 v128, 0
	v_mov_b32_e32 v129, 0

.Lg2_a_kdone3:
	s_nop 7
	s_nop 1
	v_mov_b32_e32 v176, v138
	v_mul_f32_e32 v162, 0xbfb8aa3b, v2
	v_mul_f32_e32 v163, 0xbfb8aa3b, v3
	v_mul_f32_e32 v164, 0xbfb8aa3b, v4
	v_mul_f32_e32 v165, 0xbfb8aa3b, v5
	v_exp_f32_e32 v162, v162
	v_exp_f32_e32 v163, v163
	v_exp_f32_e32 v164, v164
	v_exp_f32_e32 v165, v165
	v_add_f32_e32 v162, 1.0, v162
	v_add_f32_e32 v163, 1.0, v163
	v_add_f32_e32 v164, 1.0, v164
	v_add_f32_e32 v165, 1.0, v165
	v_rcp_f32_e32 v162, v162
	v_rcp_f32_e32 v163, v163
	v_rcp_f32_e32 v164, v164
	v_rcp_f32_e32 v165, v165
	v_mul_f32_e32 v162, v2, v162
	v_mul_f32_e32 v163, v3, v163
	v_mul_f32_e32 v164, v4, v164
	v_mul_f32_e32 v165, v5, v165
	v_mul_f32_e32 v162, v10, v162
	v_mul_f32_e32 v163, v11, v163
	v_mul_f32_e32 v164, v12, v164
	v_mul_f32_e32 v165, v13, v165
	v_cvt_pk_bf16_f32 v168, v162, v163
	v_cvt_pk_bf16_f32 v169, v164, v165
	v_mul_f32_e32 v162, 0xbfb8aa3b, v6
	v_mul_f32_e32 v163, 0xbfb8aa3b, v7
	v_mul_f32_e32 v164, 0xbfb8aa3b, v8
	v_mul_f32_e32 v165, 0xbfb8aa3b, v9
	v_exp_f32_e32 v162, v162
	v_exp_f32_e32 v163, v163
	v_exp_f32_e32 v164, v164
	v_exp_f32_e32 v165, v165
	v_add_f32_e32 v162, 1.0, v162
	v_add_f32_e32 v163, 1.0, v163
	v_add_f32_e32 v164, 1.0, v164
	v_add_f32_e32 v165, 1.0, v165
	v_rcp_f32_e32 v162, v162
	v_rcp_f32_e32 v163, v163
	v_rcp_f32_e32 v164, v164
	v_rcp_f32_e32 v165, v165
	v_mul_f32_e32 v162, v6, v162
	v_mul_f32_e32 v163, v7, v163
	v_mul_f32_e32 v164, v8, v164
	v_mul_f32_e32 v165, v9, v165
	v_mul_f32_e32 v162, v14, v162
	v_mul_f32_e32 v163, v15, v163
	v_mul_f32_e32 v164, v16, v164
	v_mul_f32_e32 v165, v17, v165
	v_cvt_pk_bf16_f32 v170, v162, v163
	v_cvt_pk_bf16_f32 v171, v164, v165
	s_nop 1
	v_permlane16_swap_b32_e32 v168, v170
	v_permlane16_swap_b32_e32 v169, v171
	global_store_dwordx4 v176, v[168:171], s[4:5] offset:0 sc1
	v_mul_f32_e32 v162, 0xbfb8aa3b, v66
	v_mul_f32_e32 v163, 0xbfb8aa3b, v67
	v_mul_f32_e32 v164, 0xbfb8aa3b, v68
	v_mul_f32_e32 v165, 0xbfb8aa3b, v69
	v_exp_f32_e32 v162, v162
	v_exp_f32_e32 v163, v163
	v_exp_f32_e32 v164, v164
	v_exp_f32_e32 v165, v165
	v_add_f32_e32 v162, 1.0, v162
	v_add_f32_e32 v163, 1.0, v163
	v_add_f32_e32 v164, 1.0, v164
	v_add_f32_e32 v165, 1.0, v165
	v_rcp_f32_e32 v162, v162
	v_rcp_f32_e32 v163, v163
	v_rcp_f32_e32 v164, v164
	v_rcp_f32_e32 v165, v165
	v_mul_f32_e32 v162, v66, v162
	v_mul_f32_e32 v163, v67, v163
	v_mul_f32_e32 v164, v68, v164
	v_mul_f32_e32 v165, v69, v165
	v_mul_f32_e32 v162, v74, v162
	v_mul_f32_e32 v163, v75, v163
	v_mul_f32_e32 v164, v76, v164
	v_mul_f32_e32 v165, v77, v165
	v_cvt_pk_bf16_f32 v172, v162, v163
	v_cvt_pk_bf16_f32 v173, v164, v165
	v_mul_f32_e32 v162, 0xbfb8aa3b, v70
	v_mul_f32_e32 v163, 0xbfb8aa3b, v71
	v_mul_f32_e32 v164, 0xbfb8aa3b, v72
	v_mul_f32_e32 v165, 0xbfb8aa3b, v73
	v_exp_f32_e32 v162, v162
	v_exp_f32_e32 v163, v163
	v_exp_f32_e32 v164, v164
	v_exp_f32_e32 v165, v165
	v_add_f32_e32 v162, 1.0, v162
	v_add_f32_e32 v163, 1.0, v163
	v_add_f32_e32 v164, 1.0, v164
	v_add_f32_e32 v165, 1.0, v165
	v_rcp_f32_e32 v162, v162
	v_rcp_f32_e32 v163, v163
	v_rcp_f32_e32 v164, v164
	v_rcp_f32_e32 v165, v165
	v_mul_f32_e32 v162, v70, v162
	v_mul_f32_e32 v163, v71, v163
	v_mul_f32_e32 v164, v72, v164
	v_mul_f32_e32 v165, v73, v165
	v_mul_f32_e32 v162, v78, v162
	v_mul_f32_e32 v163, v79, v163
	v_mul_f32_e32 v164, v80, v164
	v_mul_f32_e32 v165, v81, v165
	v_cvt_pk_bf16_f32 v174, v162, v163
	v_cvt_pk_bf16_f32 v175, v164, v165
	s_nop 1
	v_permlane16_swap_b32_e32 v172, v174
	v_permlane16_swap_b32_e32 v173, v175
	global_store_dwordx4 v176, v[172:175], s[4:5] offset:2048 sc1
	v_add_u32_e32 v176, 0x16000, v176
	v_mul_f32_e32 v162, 0xbfb8aa3b, v18
	v_mul_f32_e32 v163, 0xbfb8aa3b, v19
	v_mul_f32_e32 v164, 0xbfb8aa3b, v20
	v_mul_f32_e32 v165, 0xbfb8aa3b, v21
	v_exp_f32_e32 v162, v162
	v_exp_f32_e32 v163, v163
	v_exp_f32_e32 v164, v164
	v_exp_f32_e32 v165, v165
	v_add_f32_e32 v162, 1.0, v162
	v_add_f32_e32 v163, 1.0, v163
	v_add_f32_e32 v164, 1.0, v164
	v_add_f32_e32 v165, 1.0, v165
	v_rcp_f32_e32 v162, v162
	v_rcp_f32_e32 v163, v163
	v_rcp_f32_e32 v164, v164
	v_rcp_f32_e32 v165, v165
	v_mul_f32_e32 v162, v18, v162
	v_mul_f32_e32 v163, v19, v163
	v_mul_f32_e32 v164, v20, v164
	v_mul_f32_e32 v165, v21, v165
	v_mul_f32_e32 v162, v26, v162
	v_mul_f32_e32 v163, v27, v163
	v_mul_f32_e32 v164, v28, v164
	v_mul_f32_e32 v165, v29, v165
	v_cvt_pk_bf16_f32 v168, v162, v163
	v_cvt_pk_bf16_f32 v169, v164, v165
	v_mul_f32_e32 v162, 0xbfb8aa3b, v22
	v_mul_f32_e32 v163, 0xbfb8aa3b, v23
	v_mul_f32_e32 v164, 0xbfb8aa3b, v24
	v_mul_f32_e32 v165, 0xbfb8aa3b, v25
	v_exp_f32_e32 v162, v162
	v_exp_f32_e32 v163, v163
	v_exp_f32_e32 v164, v164
	v_exp_f32_e32 v165, v165
	v_add_f32_e32 v162, 1.0, v162
	v_add_f32_e32 v163, 1.0, v163
	v_add_f32_e32 v164, 1.0, v164
	v_add_f32_e32 v165, 1.0, v165
	v_rcp_f32_e32 v162, v162
	v_rcp_f32_e32 v163, v163
	v_rcp_f32_e32 v164, v164
	v_rcp_f32_e32 v165, v165
	v_mul_f32_e32 v162, v22, v162
	v_mul_f32_e32 v163, v23, v163
	v_mul_f32_e32 v164, v24, v164
	v_mul_f32_e32 v165, v25, v165
	v_mul_f32_e32 v162, v30, v162
	v_mul_f32_e32 v163, v31, v163
	v_mul_f32_e32 v164, v32, v164
	v_mul_f32_e32 v165, v33, v165
	v_cvt_pk_bf16_f32 v170, v162, v163
	v_cvt_pk_bf16_f32 v171, v164, v165
	s_nop 1
	v_permlane16_swap_b32_e32 v168, v170
	v_permlane16_swap_b32_e32 v169, v171
	global_store_dwordx4 v176, v[168:171], s[4:5] offset:0 sc1
	v_mul_f32_e32 v162, 0xbfb8aa3b, v82
	v_mul_f32_e32 v163, 0xbfb8aa3b, v83
	v_mul_f32_e32 v164, 0xbfb8aa3b, v84
	v_mul_f32_e32 v165, 0xbfb8aa3b, v85
	v_exp_f32_e32 v162, v162
	v_exp_f32_e32 v163, v163
	v_exp_f32_e32 v164, v164
	v_exp_f32_e32 v165, v165
	v_add_f32_e32 v162, 1.0, v162
	v_add_f32_e32 v163, 1.0, v163
	v_add_f32_e32 v164, 1.0, v164
	v_add_f32_e32 v165, 1.0, v165
	v_rcp_f32_e32 v162, v162
	v_rcp_f32_e32 v163, v163
	v_rcp_f32_e32 v164, v164
	v_rcp_f32_e32 v165, v165
	v_mul_f32_e32 v162, v82, v162
	v_mul_f32_e32 v163, v83, v163
	v_mul_f32_e32 v164, v84, v164
	v_mul_f32_e32 v165, v85, v165
	v_mul_f32_e32 v162, v90, v162
	v_mul_f32_e32 v163, v91, v163
	v_mul_f32_e32 v164, v92, v164
	v_mul_f32_e32 v165, v93, v165
	v_cvt_pk_bf16_f32 v172, v162, v163
	v_cvt_pk_bf16_f32 v173, v164, v165
	v_mul_f32_e32 v162, 0xbfb8aa3b, v86
	v_mul_f32_e32 v163, 0xbfb8aa3b, v87
	v_mul_f32_e32 v164, 0xbfb8aa3b, v88
	v_mul_f32_e32 v165, 0xbfb8aa3b, v89
	v_exp_f32_e32 v162, v162
	v_exp_f32_e32 v163, v163
	v_exp_f32_e32 v164, v164
	v_exp_f32_e32 v165, v165
	v_add_f32_e32 v162, 1.0, v162
	v_add_f32_e32 v163, 1.0, v163
	v_add_f32_e32 v164, 1.0, v164
	v_add_f32_e32 v165, 1.0, v165
	v_rcp_f32_e32 v162, v162
	v_rcp_f32_e32 v163, v163
	v_rcp_f32_e32 v164, v164
	v_rcp_f32_e32 v165, v165
	v_mul_f32_e32 v162, v86, v162
	v_mul_f32_e32 v163, v87, v163
	v_mul_f32_e32 v164, v88, v164
	v_mul_f32_e32 v165, v89, v165
	v_mul_f32_e32 v162, v94, v162
	v_mul_f32_e32 v163, v95, v163
	v_mul_f32_e32 v164, v96, v164
	v_mul_f32_e32 v165, v97, v165
	v_cvt_pk_bf16_f32 v174, v162, v163
	v_cvt_pk_bf16_f32 v175, v164, v165
	s_nop 1
	v_permlane16_swap_b32_e32 v172, v174
	v_permlane16_swap_b32_e32 v173, v175
	global_store_dwordx4 v176, v[172:175], s[4:5] offset:2048 sc1
	v_add_u32_e32 v176, 0x16000, v176
	v_mul_f32_e32 v162, 0xbfb8aa3b, v34
	v_mul_f32_e32 v163, 0xbfb8aa3b, v35
	v_mul_f32_e32 v164, 0xbfb8aa3b, v36
	v_mul_f32_e32 v165, 0xbfb8aa3b, v37
	v_exp_f32_e32 v162, v162
	v_exp_f32_e32 v163, v163
	v_exp_f32_e32 v164, v164
	v_exp_f32_e32 v165, v165
	v_add_f32_e32 v162, 1.0, v162
	v_add_f32_e32 v163, 1.0, v163
	v_add_f32_e32 v164, 1.0, v164
	v_add_f32_e32 v165, 1.0, v165
	v_rcp_f32_e32 v162, v162
	v_rcp_f32_e32 v163, v163
	v_rcp_f32_e32 v164, v164
	v_rcp_f32_e32 v165, v165
	v_mul_f32_e32 v162, v34, v162
	v_mul_f32_e32 v163, v35, v163
	v_mul_f32_e32 v164, v36, v164
	v_mul_f32_e32 v165, v37, v165
	v_mul_f32_e32 v162, v42, v162
	v_mul_f32_e32 v163, v43, v163
	v_mul_f32_e32 v164, v44, v164
	v_mul_f32_e32 v165, v45, v165
	v_cvt_pk_bf16_f32 v168, v162, v163
	v_cvt_pk_bf16_f32 v169, v164, v165
	v_mul_f32_e32 v162, 0xbfb8aa3b, v38
	v_mul_f32_e32 v163, 0xbfb8aa3b, v39
	v_mul_f32_e32 v164, 0xbfb8aa3b, v40
	v_mul_f32_e32 v165, 0xbfb8aa3b, v41
	v_exp_f32_e32 v162, v162
	v_exp_f32_e32 v163, v163
	v_exp_f32_e32 v164, v164
	v_exp_f32_e32 v165, v165
	v_add_f32_e32 v162, 1.0, v162
	v_add_f32_e32 v163, 1.0, v163
	v_add_f32_e32 v164, 1.0, v164
	v_add_f32_e32 v165, 1.0, v165
	v_rcp_f32_e32 v162, v162
	v_rcp_f32_e32 v163, v163
	v_rcp_f32_e32 v164, v164
	v_rcp_f32_e32 v165, v165
	v_mul_f32_e32 v162, v38, v162
	v_mul_f32_e32 v163, v39, v163
	v_mul_f32_e32 v164, v40, v164
	v_mul_f32_e32 v165, v41, v165
	v_mul_f32_e32 v162, v46, v162
	v_mul_f32_e32 v163, v47, v163
	v_mul_f32_e32 v164, v48, v164
	v_mul_f32_e32 v165, v49, v165
	v_cvt_pk_bf16_f32 v170, v162, v163
	v_cvt_pk_bf16_f32 v171, v164, v165
	s_nop 1
	v_permlane16_swap_b32_e32 v168, v170
	v_permlane16_swap_b32_e32 v169, v171
	global_store_dwordx4 v176, v[168:171], s[4:5] offset:0 sc1
	v_mul_f32_e32 v162, 0xbfb8aa3b, v98
	v_mul_f32_e32 v163, 0xbfb8aa3b, v99
	v_mul_f32_e32 v164, 0xbfb8aa3b, v100
	v_mul_f32_e32 v165, 0xbfb8aa3b, v101
	v_exp_f32_e32 v162, v162
	v_exp_f32_e32 v163, v163
	v_exp_f32_e32 v164, v164
	v_exp_f32_e32 v165, v165
	v_add_f32_e32 v162, 1.0, v162
	v_add_f32_e32 v163, 1.0, v163
	v_add_f32_e32 v164, 1.0, v164
	v_add_f32_e32 v165, 1.0, v165
	v_rcp_f32_e32 v162, v162
	v_rcp_f32_e32 v163, v163
	v_rcp_f32_e32 v164, v164
	v_rcp_f32_e32 v165, v165
	v_mul_f32_e32 v162, v98, v162
	v_mul_f32_e32 v163, v99, v163
	v_mul_f32_e32 v164, v100, v164
	v_mul_f32_e32 v165, v101, v165
	v_mul_f32_e32 v162, v106, v162
	v_mul_f32_e32 v163, v107, v163
	v_mul_f32_e32 v164, v108, v164
	v_mul_f32_e32 v165, v109, v165
	v_cvt_pk_bf16_f32 v172, v162, v163
	v_cvt_pk_bf16_f32 v173, v164, v165
	v_mul_f32_e32 v162, 0xbfb8aa3b, v102
	v_mul_f32_e32 v163, 0xbfb8aa3b, v103
	v_mul_f32_e32 v164, 0xbfb8aa3b, v104
	v_mul_f32_e32 v165, 0xbfb8aa3b, v105
	v_exp_f32_e32 v162, v162
	v_exp_f32_e32 v163, v163
	v_exp_f32_e32 v164, v164
	v_exp_f32_e32 v165, v165
	v_add_f32_e32 v162, 1.0, v162
	v_add_f32_e32 v163, 1.0, v163
	v_add_f32_e32 v164, 1.0, v164
	v_add_f32_e32 v165, 1.0, v165
	v_rcp_f32_e32 v162, v162
	v_rcp_f32_e32 v163, v163
	v_rcp_f32_e32 v164, v164
	v_rcp_f32_e32 v165, v165
	v_mul_f32_e32 v162, v102, v162
	v_mul_f32_e32 v163, v103, v163
	v_mul_f32_e32 v164, v104, v164
	v_mul_f32_e32 v165, v105, v165
	v_mul_f32_e32 v162, v110, v162
	v_mul_f32_e32 v163, v111, v163
	v_mul_f32_e32 v164, v112, v164
	v_mul_f32_e32 v165, v113, v165
	v_cvt_pk_bf16_f32 v174, v162, v163
	v_cvt_pk_bf16_f32 v175, v164, v165
	s_nop 1
	v_permlane16_swap_b32_e32 v172, v174
	v_permlane16_swap_b32_e32 v173, v175
	global_store_dwordx4 v176, v[172:175], s[4:5] offset:2048 sc1
	v_add_u32_e32 v176, 0x16000, v176
	v_mul_f32_e32 v162, 0xbfb8aa3b, v50
	v_mul_f32_e32 v163, 0xbfb8aa3b, v51
	v_mul_f32_e32 v164, 0xbfb8aa3b, v52
	v_mul_f32_e32 v165, 0xbfb8aa3b, v53
	v_exp_f32_e32 v162, v162
	v_exp_f32_e32 v163, v163
	v_exp_f32_e32 v164, v164
	v_exp_f32_e32 v165, v165
	v_add_f32_e32 v162, 1.0, v162
	v_add_f32_e32 v163, 1.0, v163
	v_add_f32_e32 v164, 1.0, v164
	v_add_f32_e32 v165, 1.0, v165
	v_rcp_f32_e32 v162, v162
	v_rcp_f32_e32 v163, v163
	v_rcp_f32_e32 v164, v164
	v_rcp_f32_e32 v165, v165
	v_mul_f32_e32 v162, v50, v162
	v_mul_f32_e32 v163, v51, v163
	v_mul_f32_e32 v164, v52, v164
	v_mul_f32_e32 v165, v53, v165
	v_mul_f32_e32 v162, v58, v162
	v_mul_f32_e32 v163, v59, v163
	v_mul_f32_e32 v164, v60, v164
	v_mul_f32_e32 v165, v61, v165
	v_cvt_pk_bf16_f32 v168, v162, v163
	v_cvt_pk_bf16_f32 v169, v164, v165
	v_mul_f32_e32 v162, 0xbfb8aa3b, v54
	v_mul_f32_e32 v163, 0xbfb8aa3b, v55
	v_mul_f32_e32 v164, 0xbfb8aa3b, v56
	v_mul_f32_e32 v165, 0xbfb8aa3b, v57
	v_exp_f32_e32 v162, v162
	v_exp_f32_e32 v163, v163
	v_exp_f32_e32 v164, v164
	v_exp_f32_e32 v165, v165
	v_add_f32_e32 v162, 1.0, v162
	v_add_f32_e32 v163, 1.0, v163
	v_add_f32_e32 v164, 1.0, v164
	v_add_f32_e32 v165, 1.0, v165
	v_rcp_f32_e32 v162, v162
	v_rcp_f32_e32 v163, v163
	v_rcp_f32_e32 v164, v164
	v_rcp_f32_e32 v165, v165
	v_mul_f32_e32 v162, v54, v162
	v_mul_f32_e32 v163, v55, v163
	v_mul_f32_e32 v164, v56, v164
	v_mul_f32_e32 v165, v57, v165
	v_mul_f32_e32 v162, v62, v162
	v_mul_f32_e32 v163, v63, v163
	v_mul_f32_e32 v164, v64, v164
	v_mul_f32_e32 v165, v65, v165
	v_cvt_pk_bf16_f32 v170, v162, v163
	v_cvt_pk_bf16_f32 v171, v164, v165
	s_nop 1
	v_permlane16_swap_b32_e32 v168, v170
	v_permlane16_swap_b32_e32 v169, v171
	global_store_dwordx4 v176, v[168:171], s[4:5] offset:0 sc1
	v_mul_f32_e32 v162, 0xbfb8aa3b, v114
	v_mul_f32_e32 v163, 0xbfb8aa3b, v115
	v_mul_f32_e32 v164, 0xbfb8aa3b, v116
	v_mul_f32_e32 v165, 0xbfb8aa3b, v117
	v_exp_f32_e32 v162, v162
	v_exp_f32_e32 v163, v163
	v_exp_f32_e32 v164, v164
	v_exp_f32_e32 v165, v165
	v_add_f32_e32 v162, 1.0, v162
	v_add_f32_e32 v163, 1.0, v163
	v_add_f32_e32 v164, 1.0, v164
	v_add_f32_e32 v165, 1.0, v165
	v_rcp_f32_e32 v162, v162
	v_rcp_f32_e32 v163, v163
	v_rcp_f32_e32 v164, v164
	v_rcp_f32_e32 v165, v165
	v_mul_f32_e32 v162, v114, v162
	v_mul_f32_e32 v163, v115, v163
	v_mul_f32_e32 v164, v116, v164
	v_mul_f32_e32 v165, v117, v165
	v_mul_f32_e32 v162, v122, v162
	v_mul_f32_e32 v163, v123, v163
	v_mul_f32_e32 v164, v124, v164
	v_mul_f32_e32 v165, v125, v165
	v_cvt_pk_bf16_f32 v172, v162, v163
	v_cvt_pk_bf16_f32 v173, v164, v165
	v_mul_f32_e32 v162, 0xbfb8aa3b, v118
	v_mul_f32_e32 v163, 0xbfb8aa3b, v119
	v_mul_f32_e32 v164, 0xbfb8aa3b, v120
	v_mul_f32_e32 v165, 0xbfb8aa3b, v121
	v_exp_f32_e32 v162, v162
	v_exp_f32_e32 v163, v163
	v_exp_f32_e32 v164, v164
	v_exp_f32_e32 v165, v165
	v_add_f32_e32 v162, 1.0, v162
	v_add_f32_e32 v163, 1.0, v163
	v_add_f32_e32 v164, 1.0, v164
	v_add_f32_e32 v165, 1.0, v165
	v_rcp_f32_e32 v162, v162
	v_rcp_f32_e32 v163, v163
	v_rcp_f32_e32 v164, v164
	v_rcp_f32_e32 v165, v165
	v_mul_f32_e32 v162, v118, v162
	v_mul_f32_e32 v163, v119, v163
	v_mul_f32_e32 v164, v120, v164
	v_mul_f32_e32 v165, v121, v165
	v_mul_f32_e32 v162, v126, v162
	v_mul_f32_e32 v163, v127, v163
	v_mul_f32_e32 v164, v128, v164
	v_mul_f32_e32 v165, v129, v165
	v_cvt_pk_bf16_f32 v174, v162, v163
	v_cvt_pk_bf16_f32 v175, v164, v165
	s_nop 1
	v_permlane16_swap_b32_e32 v172, v174
	v_permlane16_swap_b32_e32 v173, v175
	global_store_dwordx4 v176, v[172:175], s[4:5] offset:2048 sc1
	s_add_u32 s10, s10, 32
	s_cmp_lt_u32 s10, 64
	s_cbranch_scc1 .Lg2_a_item1
	s_cmp_lt_u32 s15, 8
	s_cbranch_scc0 .Lg2_a_noleft5
	s_lshr_b32 s12, s15, 2
	s_add_u32 s12, s12, 4
	s_mov_b32 s11, 10
	s_and_b32 s16, s15, 3
	s_lshl_b32 s16, s16, 6
	s_and_b32 s17, s14, 3
	s_mul_i32 s17, s17, 6
	s_add_u32 s12, s12, s17
	s_lshl_b32 s12, s12, 8
	s_add_u32 s12, s12, s16
	s_lshr_b32 s17, s14, 2
	s_mul_i32 s17, s17, 22
	s_lshl_b32 s11, s11, 1
	s_add_u32 s11, s11, s17
	s_lshl_b32 s16, s12, 11
	s_add_u32 s0, s24, s16
	s_addc_u32 s1, s25, 0
	s_lshl_b32 s16, s11, 18
	s_add_u32 s2, s40, s16
	s_addc_u32 s3, s41, 0
	s_mul_i32 s16, s12, 0x1600
	s_lshl_b32 s17, s11, 11
	s_add_u32 s16, s16, s17
	s_add_u32 s4, s26, s16
	s_addc_u32 s5, s27, 0
	v_lshrrev_b32_e32 v141, 8, v142
	v_lshlrev_b32_e32 v141, 17, v141
	v_sub_u32_e32 v141, v136, v141
	s_and_b32 s17, s6, 0xfff
	s_add_u32 m0, s17, 0x0
	s_nop 0
	global_load_lds_dwordx4 v141, s[0:1]
	s_add_u32 m0, s6, 0x4000
	s_nop 0
	global_load_lds_dwordx4 v136, s[2:3]
	s_add_u32 m0, s6, 0x6000
	s_nop 0
	global_load_lds_dwordx4 v137, s[2:3]
	s_add_u32 s0, s0, 1024
	s_addc_u32 s1, s1, 0
	s_add_u32 s2, s2, 1024
	s_addc_u32 s3, s3, 0
	s_add_u32 m0, s17, 0x8000
	s_nop 0
	global_load_lds_dwordx4 v141, s[0:1]
	s_add_u32 m0, s6, 0xc000
	s_nop 0
	global_load_lds_dwordx4 v136, s[2:3]
	s_add_u32 m0, s6, 0xe000
	s_nop 0
	global_load_lds_dwordx4 v137, s[2:3]
	s_add_u32 s0, s0, 1024
	s_addc_u32 s1, s1, 0
	s_add_u32 s2, s2, 1024
	s_addc_u32 s3, s3, 0
	s_add_u32 m0, s17, 0x10000
	s_nop 0
	global_load_lds_dwordx4 v141, s[0:1]
	s_add_u32 m0, s6, 0x14000
	s_nop 0
	global_load_lds_dwordx4 v136, s[2:3]
	s_add_u32 m0, s6, 0x16000
	s_nop 0
	global_load_lds_dwordx4 v137, s[2:3]
	s_add_u32 s0, s0, 1024
	s_addc_u32 s1, s1, 0
	s_add_u32 s2, s2, 1024
	s_addc_u32 s3, s3, 0
	v_lshrrev_b32_e32 v140, 7, v142
	v_lshlrev_b32_e32 v139, 12, v140
	v_sub_u32_e32 v134, v134, v139
	v_lshl_add_u32 v134, v140, 10, v134
	v_mul_u32_u24_e32 v139, 0x42000, v140
	v_sub_u32_e32 v138, v138, v139
	v_mov_b32_e32 v2, 0
	v_mov_b32_e32 v3, 0
	v_mov_b32_e32 v4, 0
	v_mov_b32_e32 v5, 0
	v_mov_b32_e32 v6, 0
	v_mov_b32_e32 v7, 0
	v_mov_b32_e32 v8, 0
	v_mov_b32_e32 v9, 0
	v_mov_b32_e32 v10, 0
	v_mov_b32_e32 v11, 0
	v_mov_b32_e32 v12, 0
	v_mov_b32_e32 v13, 0
	v_mov_b32_e32 v14, 0
	v_mov_b32_e32 v15, 0
	v_mov_b32_e32 v16, 0
	v_mov_b32_e32 v17, 0
	v_mov_b32_e32 v66, 0
	v_mov_b32_e32 v67, 0
	v_mov_b32_e32 v68, 0
	v_mov_b32_e32 v69, 0
	v_mov_b32_e32 v70, 0
	v_mov_b32_e32 v71, 0
	v_mov_b32_e32 v72, 0
	v_mov_b32_e32 v73, 0
	v_mov_b32_e32 v74, 0
	v_mov_b32_e32 v75, 0
	v_mov_b32_e32 v76, 0
	v_mov_b32_e32 v77, 0
	v_mov_b32_e32 v78, 0
	v_mov_b32_e32 v79, 0
	v_mov_b32_e32 v80, 0
	v_mov_b32_e32 v81, 0

.Lg2_a_kdone7:
	s_nop 7
	s_nop 1
	v_mov_b32_e32 v176, v138
	v_mul_f32_e32 v162, 0xbfb8aa3b, v2
	v_mul_f32_e32 v163, 0xbfb8aa3b, v3
	v_mul_f32_e32 v164, 0xbfb8aa3b, v4
	v_mul_f32_e32 v165, 0xbfb8aa3b, v5
	v_exp_f32_e32 v162, v162
	v_exp_f32_e32 v163, v163
	v_exp_f32_e32 v164, v164
	v_exp_f32_e32 v165, v165
	v_add_f32_e32 v162, 1.0, v162
	v_add_f32_e32 v163, 1.0, v163
	v_add_f32_e32 v164, 1.0, v164
	v_add_f32_e32 v165, 1.0, v165
	v_rcp_f32_e32 v162, v162
	v_rcp_f32_e32 v163, v163
	v_rcp_f32_e32 v164, v164
	v_rcp_f32_e32 v165, v165
	v_mul_f32_e32 v162, v2, v162
	v_mul_f32_e32 v163, v3, v163
	v_mul_f32_e32 v164, v4, v164
	v_mul_f32_e32 v165, v5, v165
	v_mul_f32_e32 v162, v10, v162
	v_mul_f32_e32 v163, v11, v163
	v_mul_f32_e32 v164, v12, v164
	v_mul_f32_e32 v165, v13, v165
	v_cvt_pk_bf16_f32 v168, v162, v163
	v_cvt_pk_bf16_f32 v169, v164, v165
	v_mul_f32_e32 v162, 0xbfb8aa3b, v6
	v_mul_f32_e32 v163, 0xbfb8aa3b, v7
	v_mul_f32_e32 v164, 0xbfb8aa3b, v8
	v_mul_f32_e32 v165, 0xbfb8aa3b, v9
	v_exp_f32_e32 v162, v162
	v_exp_f32_e32 v163, v163
	v_exp_f32_e32 v164, v164
	v_exp_f32_e32 v165, v165
	v_add_f32_e32 v162, 1.0, v162
	v_add_f32_e32 v163, 1.0, v163
	v_add_f32_e32 v164, 1.0, v164
	v_add_f32_e32 v165, 1.0, v165
	v_rcp_f32_e32 v162, v162
	v_rcp_f32_e32 v163, v163
	v_rcp_f32_e32 v164, v164
	v_rcp_f32_e32 v165, v165
	v_mul_f32_e32 v162, v6, v162
	v_mul_f32_e32 v163, v7, v163
	v_mul_f32_e32 v164, v8, v164
	v_mul_f32_e32 v165, v9, v165
	v_mul_f32_e32 v162, v14, v162
	v_mul_f32_e32 v163, v15, v163
	v_mul_f32_e32 v164, v16, v164
	v_mul_f32_e32 v165, v17, v165
	v_cvt_pk_bf16_f32 v170, v162, v163
	v_cvt_pk_bf16_f32 v171, v164, v165
	s_nop 1
	v_permlane16_swap_b32_e32 v168, v170
	v_permlane16_swap_b32_e32 v169, v171
	global_store_dwordx4 v176, v[168:171], s[4:5] offset:0 sc1
	v_mul_f32_e32 v162, 0xbfb8aa3b, v66
	v_mul_f32_e32 v163, 0xbfb8aa3b, v67
	v_mul_f32_e32 v164, 0xbfb8aa3b, v68
	v_mul_f32_e32 v165, 0xbfb8aa3b, v69
	v_exp_f32_e32 v162, v162
	v_exp_f32_e32 v163, v163
	v_exp_f32_e32 v164, v164
	v_exp_f32_e32 v165, v165
	v_add_f32_e32 v162, 1.0, v162
	v_add_f32_e32 v163, 1.0, v163
	v_add_f32_e32 v164, 1.0, v164
	v_add_f32_e32 v165, 1.0, v165
	v_rcp_f32_e32 v162, v162
	v_rcp_f32_e32 v163, v163
	v_rcp_f32_e32 v164, v164
	v_rcp_f32_e32 v165, v165
	v_mul_f32_e32 v162, v66, v162
	v_mul_f32_e32 v163, v67, v163
	v_mul_f32_e32 v164, v68, v164
	v_mul_f32_e32 v165, v69, v165
	v_mul_f32_e32 v162, v74, v162
	v_mul_f32_e32 v163, v75, v163
	v_mul_f32_e32 v164, v76, v164
	v_mul_f32_e32 v165, v77, v165
	v_cvt_pk_bf16_f32 v172, v162, v163
	v_cvt_pk_bf16_f32 v173, v164, v165
	v_mul_f32_e32 v162, 0xbfb8aa3b, v70
	v_mul_f32_e32 v163, 0xbfb8aa3b, v71
	v_mul_f32_e32 v164, 0xbfb8aa3b, v72
	v_mul_f32_e32 v165, 0xbfb8aa3b, v73
	v_exp_f32_e32 v162, v162
	v_exp_f32_e32 v163, v163
	v_exp_f32_e32 v164, v164
	v_exp_f32_e32 v165, v165
	v_add_f32_e32 v162, 1.0, v162
	v_add_f32_e32 v163, 1.0, v163
	v_add_f32_e32 v164, 1.0, v164
	v_add_f32_e32 v165, 1.0, v165
	v_rcp_f32_e32 v162, v162
	v_rcp_f32_e32 v163, v163
	v_rcp_f32_e32 v164, v164
	v_rcp_f32_e32 v165, v165
	v_mul_f32_e32 v162, v70, v162
	v_mul_f32_e32 v163, v71, v163
	v_mul_f32_e32 v164, v72, v164
	v_mul_f32_e32 v165, v73, v165
	v_mul_f32_e32 v162, v78, v162
	v_mul_f32_e32 v163, v79, v163
	v_mul_f32_e32 v164, v80, v164
	v_mul_f32_e32 v165, v81, v165
	v_cvt_pk_bf16_f32 v174, v162, v163
	v_cvt_pk_bf16_f32 v175, v164, v165
	s_nop 1
	v_permlane16_swap_b32_e32 v172, v174
	v_permlane16_swap_b32_e32 v173, v175
	global_store_dwordx4 v176, v[172:175], s[4:5] offset:2048 sc1

.LBB0_401:
	v_mov_b32_e32 v0, v142
	v_mov_b32_e32 v18, v142
	s_ashr_i32 s0, s9, 31
	v_lshlrev_b32_e32 v19, 4, v18
	v_bfe_i32 v3, v18, 27, 1
	s_waitcnt lgkmcnt(0)
	v_add_u32_e32 v21, 0x2000, v19
	v_lshrrev_b32_e32 v3, 22, v3
	v_ashrrev_i32_e32 v8, 31, v21
	v_add_u32_e32 v3, v19, v3
	v_lshrrev_b32_e32 v8, 22, v8
	s_lshr_b32 s0, s0, 27
	v_and_b32_e32 v3, 0xfffffc00, v3
	v_add_u32_e32 v8, v21, v8
	s_add_i32 s0, s9, s0
	v_ashrrev_i32_e32 v2, 31, v18
	v_sub_u32_e32 v3, v19, v3
	v_ashrrev_i32_e32 v8, 10, v8
	s_and_b32 s1, s0, 0xffffffe0
	v_lshrrev_b32_e32 v2, 26, v2
	v_lshrrev_b32_e32 v4, 4, v3
	v_mul_i32_i24_e32 v9, 0x400, v8
	s_sub_i32 s11, s9, s1
	s_lshl_b32 s0, s0, 2
	v_add_u32_e32 v2, v18, v2
	v_bitop3_b32 v4, v4, v3, 32 bitop3:0x6c
	v_ashrrev_i32_e32 v3, 31, v3
	v_sub_u32_e32 v9, v21, v9
	s_and_b32 s10, s0, 0xffffff80
	s_mul_i32 s0, s11, 0x108000
	v_ashrrev_i32_e32 v2, 6, v2
	v_lshrrev_b32_e32 v3, 26, v3
	v_lshrrev_b32_e32 v10, 4, v9
	s_ashr_i32 s1, s0, 31
	v_lshlrev_b32_e32 v5, 3, v2
	v_add_u32_e32 v3, v4, v3
	v_bitop3_b32 v9, v10, v9, 32 bitop3:0x6c
	s_add_u32 s14, s26, s0
	v_and_b32_e32 v5, -16, v5
	v_ashrrev_i32_e32 v3, 6, v3
	v_ashrrev_i32_e32 v11, 31, v9
	s_addc_u32 s15, s27, s1
	v_add_u32_e32 v20, v3, v5
	v_mul_i32_i24_e32 v3, 64, v3
	v_lshrrev_b32_e32 v11, 26, v11
	v_sub_u32_e32 v3, v4, v3
	v_mov_b64_e32 v[4:5], s[14:15]
	v_lshlrev_b32_e32 v10, 3, v8
	v_add_u32_e32 v11, v9, v11
	v_mad_i64_i32 v[6:7], s[14:15], v20, s67, v[4:5]
	v_add_u32_e32 v60, 0, v19
	v_and_b32_e32 v10, -16, v10
	v_ashrrev_i32_e32 v12, 6, v11
	v_readfirstlane_b32 s14, v60
	v_add_u32_e32 v22, v12, v10
	v_and_b32_e32 v10, 0xc0, v11
	s_mov_b32 m0, s14
	v_sub_u32_e32 v9, v9, v10
	v_mad_i64_i32 v[10:11], s[14:15], v22, s67, v[4:5]
	v_add_u32_e32 v12, 0x2000, v60
	v_add_u32_e32 v23, 0x4000, v19
	v_readfirstlane_b32 s14, v12
	v_ashrrev_i32_e32 v12, 31, v23
	v_lshrrev_b32_e32 v12, 22, v12
	v_add_u32_e32 v12, v23, v12
	v_ashrrev_i32_e32 v12, 10, v12
	v_mul_i32_i24_e32 v13, 0x400, v12
	v_sub_u32_e32 v13, v23, v13
	v_lshrrev_b32_e32 v14, 4, v13
	v_bitop3_b32 v13, v14, v13, 32 bitop3:0x6c
	v_ashrrev_i32_e32 v15, 31, v13
	v_lshlrev_b32_e32 v2, 5, v2
	v_lshrrev_b32_e32 v15, 26, v15
	v_and_b32_e32 v2, 32, v2
	v_ashrrev_i16_sdwa v3, v146, sext(v3) dst_sel:DWORD dst_unused:UNUSED_PAD src0_sel:DWORD src1_sel:BYTE_0
	v_lshlrev_b32_e32 v14, 3, v12
	v_add_u32_e32 v15, v13, v15
	v_add_u32_sdwa v2, v2, sext(v3) dst_sel:DWORD dst_unused:UNUSED_PAD src0_sel:DWORD src1_sel:WORD_0
	v_and_b32_e32 v14, -16, v14
	v_ashrrev_i32_e32 v16, 6, v15
	v_ashrrev_i32_e32 v3, 31, v2
	v_lshlrev_b32_e32 v8, 5, v8
	v_add_u32_e32 v24, v16, v14
	v_and_b32_e32 v14, 0xc0, v15
	s_mul_i32 s16, s10, 0x1600
	v_lshlrev_b64 v[2:3], 1, v[2:3]
	v_and_b32_e32 v8, 32, v8
	v_ashrrev_i16_sdwa v9, v146, sext(v9) dst_sel:DWORD dst_unused:UNUSED_PAD src0_sel:DWORD src1_sel:BYTE_0
	v_lshlrev_b32_e32 v12, 5, v12
	v_sub_u32_e32 v13, v13, v14
	s_mul_hi_i32 s13, s10, 0x1600
	s_add_u32 s2, s5, s16
	v_lshl_add_u64 v[6:7], v[6:7], 0, v[2:3]
	v_add_u32_sdwa v8, v8, sext(v9) dst_sel:DWORD dst_unused:UNUSED_PAD src0_sel:DWORD src1_sel:WORD_0
	v_and_b32_e32 v12, 32, v12
	v_ashrrev_i16_sdwa v13, v146, sext(v13) dst_sel:DWORD dst_unused:UNUSED_PAD src0_sel:DWORD src1_sel:BYTE_0
	s_addc_u32 s3, s6, s13
	s_waitcnt vmcnt(0)
	s_barrier
	v_ashrrev_i32_e32 v9, 31, v8
	s_mov_b32 m0, s14
	v_add_u32_sdwa v12, v12, sext(v13) dst_sel:DWORD dst_unused:UNUSED_PAD src0_sel:DWORD src1_sel:WORD_0
	v_mad_i64_i32 v[4:5], s[14:15], v24, s67, v[4:5]
	v_add_u32_e32 v14, 0x4000, v60
	v_lshlrev_b64 v[8:9], 1, v[8:9]
	v_ashrrev_i32_e32 v13, 31, v12
	v_readfirstlane_b32 s14, v14
	v_mov_b64_e32 v[14:15], s[2:3]
	v_lshl_add_u64 v[10:11], v[10:11], 0, v[8:9]
	v_lshlrev_b64 v[12:13], 1, v[12:13]
	v_mad_i64_i32 v[16:17], s[2:3], v20, s67, v[14:15]
	v_add_u32_e32 v25, 0x8000, v60
	v_lshl_add_u64 v[4:5], v[4:5], 0, v[12:13]
	s_mov_b32 m0, s14
	v_readfirstlane_b32 s2, v25
	s_mov_b32 m0, s2
	v_mad_i64_i32 v[14:15], s[2:3], v22, s67, v[14:15]
	v_add_u32_e32 v25, 0xa000, v60
	v_lshl_add_u64 v[16:17], v[16:17], 0, v[2:3]
	v_readfirstlane_b32 s2, v25
	v_add_u32_e32 v25, 0xc000, v60
	v_lshl_add_u64 v[14:15], v[14:15], 0, v[8:9]
	s_mov_b32 m0, s2
	v_readfirstlane_b32 s2, v25
	v_lshl_add_u64 v[6:7], v[6:7], 0, s[30:31]
	s_mov_b32 m0, s2
	v_lshl_add_u64 v[4:5], v[4:5], 0, s[30:31]
	v_lshl_add_u64 v[6:7], v[10:11], 0, s[30:31]
	v_add_u32_e32 v10, 0xe000, v60
	s_mov_b64 s[14:15], 0x2400100
	v_readfirstlane_b32 s2, v10
	s_mov_b32 m0, s2
	s_add_i32 s2, 0, 0xc000
	v_add_u32_e32 v6, s2, v23
	v_lshlrev_b32_e32 v7, 2, v18
	v_readfirstlane_b32 s2, v6
	v_add_u32_e32 v6, s54, v19
	s_mov_b32 m0, s2
	v_readfirstlane_b32 s2, v6
	v_add_u32_e32 v6, s54, v21
	v_lshl_add_u64 v[4:5], v[16:17], 0, s[30:31]
	s_mov_b32 m0, s2
	v_readfirstlane_b32 s2, v6
	v_lshl_add_u64 v[4:5], v[14:15], 0, s[30:31]
	s_mov_b32 m0, s2
	v_and_b32_e32 v6, 48, v18
	v_lshlrev_b32_e32 v5, 6, v18
	v_and_b32_e32 v5, 0x3c0, v5
	v_and_b32_e32 v7, 32, v7
	v_lshrrev_b32_e32 v4, 7, v18
	v_bitop3_b32 v5, v5, v7, v6 bitop3:0x36
	v_lshlrev_b32_e32 v6, 7, v18
	s_movk_i32 s2, 0x1800
	v_and_b32_e32 v6, 0x2000, v6
	v_mul_lo_u32 v4, v4, s2
	s_add_i32 s2, 0, 0x8000
	v_add3_u32 v62, v6, s2, v5
	s_add_u32 s2, s7, s16
	s_addc_u32 s3, s8, s13
	v_add3_u32 v61, v4, 0, v5
	v_mov_b64_e32 v[4:5], s[2:3]
	v_mad_i64_i32 v[6:7], s[2:3], v22, s67, v[4:5]
	v_mad_i64_i32 v[4:5], s[2:3], v20, s67, v[4:5]
	v_lshl_add_u64 v[52:53], v[4:5], 0, v[2:3]
	v_mad_i64_i32 v[4:5], s[2:3], v24, s67, v[12:13]
	v_lshl_add_u64 v[4:5], v[4:5], 0, s[0:1]
	v_mad_i64_i32 v[2:3], s[2:3], v20, s67, v[2:3]
	v_lshl_add_u64 v[54:55], v[4:5], 0, s[14:15]
	v_mad_i64_i32 v[4:5], s[2:3], v22, s67, v[8:9]
	v_lshl_add_u64 v[2:3], v[2:3], 0, s[0:1]
	v_lshl_add_u64 v[4:5], v[4:5], 0, s[0:1]
	v_lshl_add_u64 v[58:59], v[2:3], 0, s[14:15]
	v_mov_b32_e32 v2, 0
	s_mov_b32 s12, 2
	v_lshl_add_u64 v[50:51], v[6:7], 0, v[8:9]
	v_lshl_add_u64 v[56:57], v[4:5], 0, s[14:15]
	s_mov_b32 s1, 0
	s_mov_b32 s0, 42
	v_mov_b32_e32 v3, v2
	v_mov_b32_e32 v4, v2
	v_mov_b32_e32 v5, v2
	v_mov_b32_e32 v6, v2
	v_mov_b32_e32 v7, v2
	v_mov_b32_e32 v8, v2
	v_mov_b32_e32 v9, v2
	v_mov_b32_e32 v10, v2
	v_mov_b32_e32 v11, v2
	v_mov_b32_e32 v12, v2
	v_mov_b32_e32 v13, v2
	v_mov_b32_e32 v14, v2
	v_mov_b32_e32 v15, v2
	v_mov_b32_e32 v16, v2
	v_mov_b32_e32 v17, v2
	v_mov_b32_e32 v18, v2
	v_mov_b32_e32 v19, v2
	v_mov_b32_e32 v20, v2
	v_mov_b32_e32 v21, v2
	v_mov_b32_e32 v22, v2
	v_mov_b32_e32 v23, v2
	v_mov_b32_e32 v24, v2
	v_mov_b32_e32 v25, v2
	v_mov_b32_e32 v26, v2
	v_mov_b32_e32 v27, v2
	v_mov_b32_e32 v28, v2
	v_mov_b32_e32 v29, v2
	v_mov_b32_e32 v30, v2
	v_mov_b32_e32 v31, v2
	v_mov_b32_e32 v32, v2
	v_mov_b32_e32 v33, v2
	v_mov_b32_e32 v34, v2
	v_mov_b32_e32 v35, v2
	v_mov_b32_e32 v36, v2
	v_mov_b32_e32 v37, v2
	v_mov_b32_e32 v38, v2
	v_mov_b32_e32 v39, v2
	v_mov_b32_e32 v40, v2
	v_mov_b32_e32 v41, v2
	v_mov_b32_e32 v42, v2
	v_mov_b32_e32 v43, v2
	v_mov_b32_e32 v44, v2
	v_mov_b32_e32 v45, v2
	v_mov_b32_e32 v46, v2
	v_mov_b32_e32 v47, v2
	v_mov_b32_e32 v48, v2
	v_mov_b32_e32 v49, v2
.LBB0_402:
	v_readlane_b32 s42, v214, 57
	s_and_b32 s43, s9, 31
	s_mul_i32 s43, s43, 0x108000
	s_add_u32 s38, s26, s43
	s_addc_u32 s39, s27, 0
	s_mul_hi_u32 s2, s42, 0x3500000
	s_mul_i32 s42, s42, 0x3500000
	s_add_u32 s40, s48, s42
	s_addc_u32 s41, s49, s2
	s_add_u32 s40, s40, 0x100ce000
	s_addc_u32 s41, s41, 0
	s_lshr_b32 s43, s9, 5
	s_mul_i32 s43, s43, 0xb0000
	s_add_u32 s40, s40, s43
	s_addc_u32 s41, s41, 0
	v_and_b32_e32 v226, 63, v142
	v_lshlrev_b32_e32 v222, 4, v226
	v_lshrrev_b32_e32 v227, 5, v226
	v_lshlrev_b32_e32 v227, 5, v227
	v_xor_b32_e32 v222, v222, v227
	v_lshrrev_b32_e32 v226, 6, v142
	v_and_b32_e32 v227, 1, v226
	v_lshrrev_b32_e32 v226, 1, v226
	v_lshl_add_u32 v222, v227, 10, v222
	v_mul_u32_u24_e32 v226, 0x16000, v226
	v_add_u32_e32 v222, v222, v226
	v_add_u32_e32 v223, 0x58000, v222
	v_add_u32_e32 v224, 0x58000, v223
	v_add_u32_e32 v218, 0x0, v60
	s_nop 0
	v_readfirstlane_b32 s2, v218
	s_add_u32 m0, s2, 0x0
	s_nop 0
	global_load_lds_dwordx4 v222, s[38:39]
	s_add_u32 m0, s2, 0x2000
	s_nop 0
	global_load_lds_dwordx4 v223, s[38:39]
	s_add_u32 m0, s2, 0x4000
	s_nop 0
	global_load_lds_dwordx4 v224, s[38:39]
	s_add_u32 m0, s2, 0x8000
	s_nop 0
	global_load_lds_dwordx4 v222, s[40:41]
	s_add_u32 m0, s2, 0xa000
	s_nop 0
	global_load_lds_dwordx4 v223, s[40:41]
	s_add_u32 s38, s38, 0x800
	s_addc_u32 s39, s39, 0
	s_add_u32 s40, s40, 0x800
	s_addc_u32 s41, s41, 0
	v_add_u32_e32 v218, 0xc000, v60
	s_nop 0
	v_readfirstlane_b32 s2, v218
	s_add_u32 m0, s2, 0x0
	s_nop 0
	global_load_lds_dwordx4 v222, s[38:39]
	s_add_u32 m0, s2, 0x2000
	s_nop 0
	global_load_lds_dwordx4 v223, s[38:39]
	s_add_u32 m0, s2, 0x4000
	s_nop 0
	global_load_lds_dwordx4 v224, s[38:39]
	s_add_u32 m0, s2, 0x8000
	s_nop 0
	global_load_lds_dwordx4 v222, s[40:41]
	s_add_u32 m0, s2, 0xa000
	s_nop 0
	global_load_lds_dwordx4 v223, s[40:41]
	s_add_u32 s38, s38, 0x800
	s_addc_u32 s39, s39, 0
	s_add_u32 s40, s40, 0x800
	s_addc_u32 s41, s41, 0
	s_mov_b32 s42, 42
.Lgb_dn0:
	s_waitcnt vmcnt(5)
	s_barrier
	s_mul_i32 s2, s1, 0xc000
	v_add_u32_e32 v220, s2, v61
	v_add_u32_e32 v221, s2, v62
	ds_read_b128 v[64:67], v220 offset:0
	ds_read_b128 v[68:71], v220 offset:2048
	ds_read_b128 v[72:75], v220 offset:4096
	ds_read_b128 v[76:79], v221 offset:0
	ds_read_b128 v[80:83], v221 offset:2048
	ds_read_b128 v[84:87], v221 offset:4096
	ds_read_b128 v[88:91], v221 offset:6144
	s_mul_i32 s2, s12, 0xc000
	v_add_u32_e32 v218, s2, v60
	s_nop 0
	v_readfirstlane_b32 s2, v218
	s_add_u32 m0, s2, 0x0
	s_nop 0
	global_load_lds_dwordx4 v222, s[38:39]
	s_add_u32 m0, s2, 0x2000
	s_nop 0
	global_load_lds_dwordx4 v223, s[38:39]
	s_add_u32 m0, s2, 0x4000
	s_nop 0
	global_load_lds_dwordx4 v224, s[38:39]
	s_add_u32 m0, s2, 0x8000
	s_nop 0
	global_load_lds_dwordx4 v222, s[40:41]
	s_add_u32 m0, s2, 0xa000
	s_nop 0
	global_load_lds_dwordx4 v223, s[40:41]
	ds_read_b128 v[92:95], v220 offset:1024
	ds_read_b128 v[96:99], v220 offset:3072
	ds_read_b128 v[100:103], v220 offset:5120
	ds_read_b128 v[104:107], v221 offset:1024
	ds_read_b128 v[108:111], v221 offset:3072
	ds_read_b128 v[112:115], v221 offset:5120
	ds_read_b128 v[116:119], v221 offset:7168
	s_waitcnt lgkmcnt(7)
	v_mfma_f32_16x16x32_bf16 v[46:49], v[76:79], v[64:67], v[46:49]
	v_mfma_f32_16x16x32_bf16 v[42:45], v[80:83], v[64:67], v[42:45]
	v_mfma_f32_16x16x32_bf16 v[38:41], v[84:87], v[64:67], v[38:41]
	v_mfma_f32_16x16x32_bf16 v[34:37], v[88:91], v[64:67], v[34:37]
	v_mfma_f32_16x16x32_bf16 v[30:33], v[76:79], v[68:71], v[30:33]
	v_mfma_f32_16x16x32_bf16 v[26:29], v[80:83], v[68:71], v[26:29]
	v_mfma_f32_16x16x32_bf16 v[22:25], v[84:87], v[68:71], v[22:25]
	v_mfma_f32_16x16x32_bf16 v[18:21], v[88:91], v[68:71], v[18:21]
	v_mfma_f32_16x16x32_bf16 v[14:17], v[76:79], v[72:75], v[14:17]
	v_mfma_f32_16x16x32_bf16 v[10:13], v[80:83], v[72:75], v[10:13]
	v_mfma_f32_16x16x32_bf16 v[6:9], v[84:87], v[72:75], v[6:9]
	v_mfma_f32_16x16x32_bf16 v[2:5], v[88:91], v[72:75], v[2:5]
	s_waitcnt lgkmcnt(0)
	s_add_i32 s2, s1, 1
	s_cmp_lg_u32 s1, 2
	s_cselect_b32 s1, s2, 0
	s_add_i32 s2, s12, 1
	s_cmp_lg_u32 s12, 2
	s_cselect_b32 s12, s2, 0
	s_add_u32 s38, s38, 0x800
	s_addc_u32 s39, s39, 0
	s_add_u32 s40, s40, 0x800
	s_addc_u32 s41, s41, 0
	s_sub_u32 s42, s42, 1
.Lgbl_dn0:
	s_waitcnt vmcnt(5)
	s_barrier
	s_mul_i32 s2, s1, 0xc000
	v_add_u32_e32 v220, s2, v61
	v_add_u32_e32 v221, s2, v62
	ds_read_b128 v[64:67], v220 offset:0
	ds_read_b128 v[68:71], v220 offset:2048
	ds_read_b128 v[72:75], v220 offset:4096
	ds_read_b128 v[76:79], v221 offset:0
	ds_read_b128 v[80:83], v221 offset:2048
	ds_read_b128 v[84:87], v221 offset:4096
	ds_read_b128 v[88:91], v221 offset:6144
	s_mul_i32 s2, s12, 0xc000
	v_add_u32_e32 v218, s2, v60
	s_nop 0
	v_readfirstlane_b32 s2, v218
	v_mfma_f32_16x16x32_bf16 v[46:49], v[104:107], v[92:95], v[46:49]
	v_mfma_f32_16x16x32_bf16 v[42:45], v[108:111], v[92:95], v[42:45]
	s_add_u32 m0, s2, 0x0
	s_nop 0
	global_load_lds_dwordx4 v222, s[38:39]
	v_mfma_f32_16x16x32_bf16 v[38:41], v[112:115], v[92:95], v[38:41]
	v_mfma_f32_16x16x32_bf16 v[34:37], v[116:119], v[92:95], v[34:37]
	s_add_u32 m0, s2, 0x2000
	s_nop 0
	global_load_lds_dwordx4 v223, s[38:39]
	v_mfma_f32_16x16x32_bf16 v[30:33], v[104:107], v[96:99], v[30:33]
	v_mfma_f32_16x16x32_bf16 v[26:29], v[108:111], v[96:99], v[26:29]
	s_add_u32 m0, s2, 0x4000
	s_nop 0
	global_load_lds_dwordx4 v224, s[38:39]
	v_mfma_f32_16x16x32_bf16 v[22:25], v[112:115], v[96:99], v[22:25]
	v_mfma_f32_16x16x32_bf16 v[18:21], v[116:119], v[96:99], v[18:21]
	s_add_u32 m0, s2, 0x8000
	s_nop 0
	global_load_lds_dwordx4 v222, s[40:41]
	v_mfma_f32_16x16x32_bf16 v[14:17], v[104:107], v[100:103], v[14:17]
	v_mfma_f32_16x16x32_bf16 v[10:13], v[108:111], v[100:103], v[10:13]
	s_add_u32 m0, s2, 0xa000
	s_nop 0
	global_load_lds_dwordx4 v223, s[40:41]
	v_mfma_f32_16x16x32_bf16 v[6:9], v[112:115], v[100:103], v[6:9]
	v_mfma_f32_16x16x32_bf16 v[2:5], v[116:119], v[100:103], v[2:5]
	ds_read_b128 v[92:95], v220 offset:1024
	ds_read_b128 v[96:99], v220 offset:3072
	ds_read_b128 v[100:103], v220 offset:5120
	ds_read_b128 v[104:107], v221 offset:1024
	ds_read_b128 v[108:111], v221 offset:3072
	ds_read_b128 v[112:115], v221 offset:5120
	ds_read_b128 v[116:119], v221 offset:7168
	s_waitcnt lgkmcnt(7)
	v_mfma_f32_16x16x32_bf16 v[46:49], v[76:79], v[64:67], v[46:49]
	v_mfma_f32_16x16x32_bf16 v[42:45], v[80:83], v[64:67], v[42:45]
	v_mfma_f32_16x16x32_bf16 v[38:41], v[84:87], v[64:67], v[38:41]
	v_mfma_f32_16x16x32_bf16 v[34:37], v[88:91], v[64:67], v[34:37]
	v_mfma_f32_16x16x32_bf16 v[30:33], v[76:79], v[68:71], v[30:33]
	v_mfma_f32_16x16x32_bf16 v[26:29], v[80:83], v[68:71], v[26:29]
	v_mfma_f32_16x16x32_bf16 v[22:25], v[84:87], v[68:71], v[22:25]
	v_mfma_f32_16x16x32_bf16 v[18:21], v[88:91], v[68:71], v[18:21]
	v_mfma_f32_16x16x32_bf16 v[14:17], v[76:79], v[72:75], v[14:17]
	v_mfma_f32_16x16x32_bf16 v[10:13], v[80:83], v[72:75], v[10:13]
	v_mfma_f32_16x16x32_bf16 v[6:9], v[84:87], v[72:75], v[6:9]
	v_mfma_f32_16x16x32_bf16 v[2:5], v[88:91], v[72:75], v[2:5]
	s_waitcnt lgkmcnt(0)
	s_add_i32 s2, s1, 1
	s_cmp_lg_u32 s1, 2
	s_cselect_b32 s1, s2, 0
	s_add_i32 s2, s12, 1
	s_cmp_lg_u32 s12, 2
	s_cselect_b32 s12, s2, 0
	s_add_u32 s38, s38, 0x800
	s_addc_u32 s39, s39, 0
	s_add_u32 s40, s40, 0x800
	s_addc_u32 s41, s41, 0
	s_sub_u32 s42, s42, 1
	s_cmp_lg_u32 s42, 0
	s_cbranch_scc1 .Lgbl_dn0
	s_waitcnt vmcnt(5)
	s_barrier
	s_mul_i32 s2, s1, 0xc000
	v_add_u32_e32 v220, s2, v61
	v_add_u32_e32 v221, s2, v62
	ds_read_b128 v[64:67], v220 offset:0
	ds_read_b128 v[68:71], v220 offset:2048
	ds_read_b128 v[72:75], v220 offset:4096
	ds_read_b128 v[76:79], v221 offset:0
	ds_read_b128 v[80:83], v221 offset:2048
	ds_read_b128 v[84:87], v221 offset:4096
	ds_read_b128 v[88:91], v221 offset:6144
	v_mfma_f32_16x16x32_bf16 v[46:49], v[104:107], v[92:95], v[46:49]
	v_mfma_f32_16x16x32_bf16 v[42:45], v[108:111], v[92:95], v[42:45]
	v_mfma_f32_16x16x32_bf16 v[38:41], v[112:115], v[92:95], v[38:41]
	v_mfma_f32_16x16x32_bf16 v[34:37], v[116:119], v[92:95], v[34:37]
	v_mfma_f32_16x16x32_bf16 v[30:33], v[104:107], v[96:99], v[30:33]
	v_mfma_f32_16x16x32_bf16 v[26:29], v[108:111], v[96:99], v[26:29]
	v_mfma_f32_16x16x32_bf16 v[22:25], v[112:115], v[96:99], v[22:25]
	v_mfma_f32_16x16x32_bf16 v[18:21], v[116:119], v[96:99], v[18:21]
	v_mfma_f32_16x16x32_bf16 v[14:17], v[104:107], v[100:103], v[14:17]
	v_mfma_f32_16x16x32_bf16 v[10:13], v[108:111], v[100:103], v[10:13]
	v_mfma_f32_16x16x32_bf16 v[6:9], v[112:115], v[100:103], v[6:9]
	v_mfma_f32_16x16x32_bf16 v[2:5], v[116:119], v[100:103], v[2:5]
	ds_read_b128 v[92:95], v220 offset:1024
	ds_read_b128 v[96:99], v220 offset:3072
	ds_read_b128 v[100:103], v220 offset:5120
	ds_read_b128 v[104:107], v221 offset:1024
	ds_read_b128 v[108:111], v221 offset:3072
	ds_read_b128 v[112:115], v221 offset:5120
	ds_read_b128 v[116:119], v221 offset:7168
	s_waitcnt lgkmcnt(7)
	v_mfma_f32_16x16x32_bf16 v[46:49], v[76:79], v[64:67], v[46:49]
	v_mfma_f32_16x16x32_bf16 v[42:45], v[80:83], v[64:67], v[42:45]
	v_mfma_f32_16x16x32_bf16 v[38:41], v[84:87], v[64:67], v[38:41]
	v_mfma_f32_16x16x32_bf16 v[34:37], v[88:91], v[64:67], v[34:37]
	v_mfma_f32_16x16x32_bf16 v[30:33], v[76:79], v[68:71], v[30:33]
	v_mfma_f32_16x16x32_bf16 v[26:29], v[80:83], v[68:71], v[26:29]
	v_mfma_f32_16x16x32_bf16 v[22:25], v[84:87], v[68:71], v[22:25]
	v_mfma_f32_16x16x32_bf16 v[18:21], v[88:91], v[68:71], v[18:21]
	v_mfma_f32_16x16x32_bf16 v[14:17], v[76:79], v[72:75], v[14:17]
	v_mfma_f32_16x16x32_bf16 v[10:13], v[80:83], v[72:75], v[10:13]
	v_mfma_f32_16x16x32_bf16 v[6:9], v[84:87], v[72:75], v[6:9]
	v_mfma_f32_16x16x32_bf16 v[2:5], v[88:91], v[72:75], v[2:5]
	s_waitcnt lgkmcnt(0)
	s_add_i32 s2, s1, 1
	s_cmp_lg_u32 s1, 2
	s_cselect_b32 s1, s2, 0
	s_add_i32 s2, s12, 1
	s_cmp_lg_u32 s12, 2
	s_cselect_b32 s12, s2, 0
	s_waitcnt vmcnt(0)
	s_barrier
	s_mul_i32 s2, s1, 0xc000
	v_add_u32_e32 v220, s2, v61
	v_add_u32_e32 v221, s2, v62
	ds_read_b128 v[64:67], v220 offset:0
	ds_read_b128 v[68:71], v220 offset:2048
	ds_read_b128 v[72:75], v220 offset:4096
	ds_read_b128 v[76:79], v221 offset:0
	ds_read_b128 v[80:83], v221 offset:2048
	ds_read_b128 v[84:87], v221 offset:4096
	ds_read_b128 v[88:91], v221 offset:6144
	v_mfma_f32_16x16x32_bf16 v[46:49], v[104:107], v[92:95], v[46:49]
	v_mfma_f32_16x16x32_bf16 v[42:45], v[108:111], v[92:95], v[42:45]
	v_mfma_f32_16x16x32_bf16 v[38:41], v[112:115], v[92:95], v[38:41]
	v_mfma_f32_16x16x32_bf16 v[34:37], v[116:119], v[92:95], v[34:37]
	v_mfma_f32_16x16x32_bf16 v[30:33], v[104:107], v[96:99], v[30:33]
	v_mfma_f32_16x16x32_bf16 v[26:29], v[108:111], v[96:99], v[26:29]
	v_mfma_f32_16x16x32_bf16 v[22:25], v[112:115], v[96:99], v[22:25]
	v_mfma_f32_16x16x32_bf16 v[18:21], v[116:119], v[96:99], v[18:21]
	v_mfma_f32_16x16x32_bf16 v[14:17], v[104:107], v[100:103], v[14:17]
	v_mfma_f32_16x16x32_bf16 v[10:13], v[108:111], v[100:103], v[10:13]
	v_mfma_f32_16x16x32_bf16 v[6:9], v[112:115], v[100:103], v[6:9]
	v_mfma_f32_16x16x32_bf16 v[2:5], v[116:119], v[100:103], v[2:5]
	ds_read_b128 v[92:95], v220 offset:1024
	ds_read_b128 v[96:99], v220 offset:3072
	ds_read_b128 v[100:103], v220 offset:5120
	ds_read_b128 v[104:107], v221 offset:1024
	ds_read_b128 v[108:111], v221 offset:3072
	ds_read_b128 v[112:115], v221 offset:5120
	ds_read_b128 v[116:119], v221 offset:7168
	s_waitcnt lgkmcnt(7)
	v_mfma_f32_16x16x32_bf16 v[46:49], v[76:79], v[64:67], v[46:49]
	v_mfma_f32_16x16x32_bf16 v[42:45], v[80:83], v[64:67], v[42:45]
	v_mfma_f32_16x16x32_bf16 v[38:41], v[84:87], v[64:67], v[38:41]
	v_mfma_f32_16x16x32_bf16 v[34:37], v[88:91], v[64:67], v[34:37]
	v_mfma_f32_16x16x32_bf16 v[30:33], v[76:79], v[68:71], v[30:33]
	v_mfma_f32_16x16x32_bf16 v[26:29], v[80:83], v[68:71], v[26:29]
	v_mfma_f32_16x16x32_bf16 v[22:25], v[84:87], v[68:71], v[22:25]
	v_mfma_f32_16x16x32_bf16 v[18:21], v[88:91], v[68:71], v[18:21]
	v_mfma_f32_16x16x32_bf16 v[14:17], v[76:79], v[72:75], v[14:17]
	v_mfma_f32_16x16x32_bf16 v[10:13], v[80:83], v[72:75], v[10:13]
	v_mfma_f32_16x16x32_bf16 v[6:9], v[84:87], v[72:75], v[6:9]
	v_mfma_f32_16x16x32_bf16 v[2:5], v[88:91], v[72:75], v[2:5]
	s_waitcnt lgkmcnt(0)
	s_add_i32 s2, s1, 1
	s_cmp_lg_u32 s1, 2
	s_cselect_b32 s1, s2, 0
	s_add_i32 s2, s12, 1
	s_cmp_lg_u32 s12, 2
	s_cselect_b32 s12, s2, 0
	v_mfma_f32_16x16x32_bf16 v[46:49], v[104:107], v[92:95], v[46:49]
	v_mfma_f32_16x16x32_bf16 v[42:45], v[108:111], v[92:95], v[42:45]
	v_mfma_f32_16x16x32_bf16 v[38:41], v[112:115], v[92:95], v[38:41]
	v_mfma_f32_16x16x32_bf16 v[34:37], v[116:119], v[92:95], v[34:37]
	v_mfma_f32_16x16x32_bf16 v[30:33], v[104:107], v[96:99], v[30:33]
	v_mfma_f32_16x16x32_bf16 v[26:29], v[108:111], v[96:99], v[26:29]
	v_mfma_f32_16x16x32_bf16 v[22:25], v[112:115], v[96:99], v[22:25]
	v_mfma_f32_16x16x32_bf16 v[18:21], v[116:119], v[96:99], v[18:21]
	v_mfma_f32_16x16x32_bf16 v[14:17], v[104:107], v[100:103], v[14:17]
	v_mfma_f32_16x16x32_bf16 v[10:13], v[108:111], v[100:103], v[10:13]
	v_mfma_f32_16x16x32_bf16 v[6:9], v[112:115], v[100:103], v[6:9]
	v_mfma_f32_16x16x32_bf16 v[2:5], v[116:119], v[100:103], v[2:5]
.Lgd_dn0:
	s_nop 7
	s_nop 1
	v_mov_b32_e32 v50, v48
	v_mov_b32_e32 v51, v49
	v_mov_b32_e32 v52, v42
	v_mov_b32_e32 v53, v43
	v_mov_b32_e32 v54, v44
	v_mov_b32_e32 v55, v45
	v_mov_b32_e32 v56, v38
	v_mov_b32_e32 v57, v39
	v_mov_b32_e32 v58, v40
	v_mov_b32_e32 v59, v41
	v_mov_b32_e32 v48, v46
	v_mov_b32_e32 v49, v47
	s_mulk_i32 s11, 0xc0
	v_and_b32_e32 v112, 64, v0
	v_ashrrev_i32_e32 v106, 7, v0
	s_nop 7
	v_readlane_b32 s68, v214, 57
	s_and_b32 s2, s9, 31
	s_mul_i32 s2, s2, 192
	s_lshr_b32 s3, s9, 5
	s_lshl_b32 s3, s3, 7
	s_mul_i32 s10, s68, 0x1b000
	s_add_u32 s10, s10, 0x2000
	s_add_u32 s38, s34, s10
	s_addc_u32 s39, s35, 0
	v_lshrrev_b32_e32 v128, 6, v142
	v_and_b32_e32 v129, 1, v128
	v_lshrrev_b32_e32 v128, 1, v128
	v_lshlrev_b32_e32 v66, 6, v129
	v_lshrrev_b32_e32 v129, 4, v142
	v_and_b32_e32 v129, 3, v129
	v_lshl_add_u32 v66, v129, 2, v66
	v_add_u32_e32 v66, s3, v66
	v_lshlrev_b32_e32 v66, 2, v66
	v_mul_u32_u24_e32 v67, 48, v128
	v_and_b32_e32 v129, 15, v142
	v_add3_u32 v67, v67, v129, s2
	v_add_u32_e32 v128, 0, v67
	v_lshl_add_u32 v141, v128, 12, v66
	v_add_u32_e32 v129, 0xfffff000, v128
	v_lshrrev_b32_e32 v129, 10, v129
	v_add_u32_e32 v129, 1, v129
	v_cmp_gt_u32_e32 vcc, 0x1000, v128
	v_cndmask_b32_e64 v129, v129, 0, vcc
	v_mul_u32_u24_e32 v129, 0x9000, v129
	v_add_u32_e32 v134, v129, v66
	global_load_dwordx4 v[68:71], v134, s[38:39] offset:0
	global_load_dwordx4 v[72:75], v134, s[38:39] offset:64
	global_load_dwordx4 v[76:79], v134, s[38:39] offset:128
	global_load_dwordx4 v[80:83], v134, s[38:39] offset:192
	v_add_u32_e32 v128, 16, v67
	v_lshl_add_u32 v162, v128, 12, v66
	v_add_u32_e32 v129, 0xfffff000, v128
	v_lshrrev_b32_e32 v129, 10, v129
	v_add_u32_e32 v129, 1, v129
	v_cmp_gt_u32_e32 vcc, 0x1000, v128
	v_cndmask_b32_e64 v129, v129, 0, vcc
	v_mul_u32_u24_e32 v129, 0x9000, v129
	v_add_u32_e32 v135, v129, v66
	global_load_dwordx4 v[84:87], v135, s[38:39] offset:0
	global_load_dwordx4 v[88:91], v135, s[38:39] offset:64
	global_load_dwordx4 v[92:95], v135, s[38:39] offset:128
	global_load_dwordx4 v[96:99], v135, s[38:39] offset:192
	v_add_u32_e32 v128, 32, v67
	v_lshl_add_u32 v163, v128, 12, v66
	v_add_u32_e32 v129, 0xfffff000, v128
	v_lshrrev_b32_e32 v129, 10, v129
	v_add_u32_e32 v129, 1, v129
	v_cmp_gt_u32_e32 vcc, 0x1000, v128
	v_cndmask_b32_e64 v129, v129, 0, vcc
	v_mul_u32_u24_e32 v129, 0x9000, v129
	v_add_u32_e32 v140, v129, v66
	global_load_dwordx4 v[100:103], v140, s[38:39] offset:0
	global_load_dwordx4 v[104:107], v140, s[38:39] offset:64
	global_load_dwordx4 v[108:111], v140, s[38:39] offset:128
	global_load_dwordx4 v[112:115], v140, s[38:39] offset:192
	s_cmp_lg_u32 s68, 0
	s_cbranch_scc1 .Lres_d0_ws
	v_readlane_b32 s10, v217, 1
	v_readlane_b32 s11, v217, 2
	s_sub_u32 s10, s10, 0xd0
	s_subb_u32 s11, s11, 0
	s_load_dwordx4 s[40:43], s[10:11], 0x0
	s_waitcnt lgkmcnt(0)
	s_sub_u32 s42, s42, 0x1000000
	s_subb_u32 s43, s43, 0
	v_add_u32_e32 v128, 0, v67
	v_cmp_gt_u32_e32 vcc, 0x1000, v128
	v_mov_b32_e32 v196, s42
	v_mov_b32_e32 v197, s43
	v_mov_b32_e32 v198, s40
	v_mov_b32_e32 v199, s41
	v_cndmask_b32_e32 v196, v196, v198, vcc
	v_cndmask_b32_e32 v197, v197, v199, vcc
	v_add_co_u32_e32 v200, vcc, v196, v141
	s_nop 1
	v_addc_co_u32_e32 v201, vcc, 0, v197, vcc
	global_load_dwordx4 v[116:119], v[200:201], off offset:0
	global_load_dwordx4 v[120:123], v[200:201], off offset:64
	global_load_dwordx4 v[124:127], v[200:201], off offset:128
	global_load_dwordx4 v[136:139], v[200:201], off offset:192
	v_add_u32_e32 v128, 16, v67
	v_cmp_gt_u32_e32 vcc, 0x1000, v128
	v_mov_b32_e32 v196, s42
	v_mov_b32_e32 v197, s43
	v_mov_b32_e32 v198, s40
	v_mov_b32_e32 v199, s41
	v_cndmask_b32_e32 v196, v196, v198, vcc
	v_cndmask_b32_e32 v197, v197, v199, vcc
	v_add_co_u32_e32 v202, vcc, v196, v162
	s_nop 1
	v_addc_co_u32_e32 v203, vcc, 0, v197, vcc
	global_load_dwordx4 v[164:167], v[202:203], off offset:0
	global_load_dwordx4 v[168:171], v[202:203], off offset:64
	global_load_dwordx4 v[172:175], v[202:203], off offset:128
	global_load_dwordx4 v[176:179], v[202:203], off offset:192
	v_add_u32_e32 v128, 32, v67
	v_cmp_gt_u32_e32 vcc, 0x1000, v128
	v_mov_b32_e32 v196, s42
	v_mov_b32_e32 v197, s43
	v_mov_b32_e32 v198, s40
	v_mov_b32_e32 v199, s41
	v_cndmask_b32_e32 v196, v196, v198, vcc
	v_cndmask_b32_e32 v197, v197, v199, vcc
	v_add_co_u32_e32 v204, vcc, v196, v163
	s_nop 1
	v_addc_co_u32_e32 v205, vcc, 0, v197, vcc
	global_load_dwordx4 v[180:183], v[204:205], off offset:0
	global_load_dwordx4 v[184:187], v[204:205], off offset:64
	global_load_dwordx4 v[188:191], v[204:205], off offset:128
	global_load_dwordx4 v[192:195], v[204:205], off offset:192
	s_branch .Lres_d0_ld

.LBB0_405:
	s_andn2_b64 vcc, exec, s[0:1]
	s_mov_b64 s[2:3], 0
	s_cbranch_vccnz .LBB0_417
	s_cmp_gt_i32 s21, 0
	s_mov_b64 s[0:1], -1
	s_cbranch_scc0 .LBB0_429
	v_readlane_b32 s11, v217, 0
	v_readlane_b32 s12, v214, 57
	s_and_b32 s14, s11, 7
	s_lshr_b32 s15, s11, 3
	s_mul_hi_u32 s16, s12, 0x3500000
	s_mul_i32 s12, s12, 0x3500000
	s_add_u32 s40, s48, s12
	s_addc_u32 s41, s49, s16
	s_add_u32 s40, s40, 0xf5ce000
	s_addc_u32 s41, s41, 0
	v_and_b32_e32 v141, 15, v142
	v_lshrrev_b32_e32 v139, 4, v142
	v_and_b32_e32 v139, 3, v139
	v_lshlrev_b32_e32 v140, 6, v141
	v_lshl_add_u32 v140, v139, 4, v140
	v_lshrrev_b32_e32 v139, 3, v141
	v_lshlrev_b32_e32 v139, 5, v139
	v_xor_b32_e32 v135, v140, v139
	v_lshrrev_b32_e32 v139, 7, v142
	v_lshl_add_u32 v134, v139, 12, v135
	v_lshrrev_b32_e32 v139, 6, v142
	v_and_b32_e32 v139, 1, v139
	v_lshl_add_u32 v135, v139, 12, v135
	v_add_u32_e32 v135, 0x4000, v135
	v_and_b32_e32 v141, 63, v142
	v_lshrrev_b32_e32 v139, 2, v141
	v_lshrrev_b32_e32 v140, 6, v142
	v_lshlrev_b32_e32 v139, 6, v139
	v_lshl_add_u32 v139, v140, 15, v139
	v_and_b32_e32 v140, 3, v141
	v_lshlrev_b32_e32 v140, 4, v140
	v_lshrrev_b32_e32 v141, 5, v141
	v_lshlrev_b32_e32 v141, 5, v141
	v_xor_b32_e32 v140, v140, v141
	v_add_u32_e32 v136, v139, v140
	v_add_u32_e32 v137, 0x40000, v136
	v_lshrrev_b32_e32 v139, 7, v142
	v_and_b32_e32 v141, 15, v142
	v_mul_u32_u24_e32 v139, 0x58000, v139
	v_lshl_add_u32 v139, v141, 6, v139
	v_lshrrev_b32_e32 v140, 6, v142
	v_and_b32_e32 v140, 1, v140
	v_lshlrev_b32_e32 v140, 10, v140
	v_lshrrev_b32_e32 v141, 4, v142
	v_and_b32_e32 v141, 3, v141
	v_lshl_add_u32 v140, v141, 3, v140
	v_add_u32_e32 v138, v139, v140
	v_and_b32_e32 v141, 1, v141
	v_mul_u32_u24_e32 v141, 24, v141
	v_add_u32_e32 v138, v138, v141
	v_lshlrev_b32_e32 v161, 11, v142
	v_lshrrev_b32_e32 v141, 6, v142
	v_lshlrev_b32_e32 v141, 10, v141
	s_nop 0
	v_readfirstlane_b32 s6, v141
	s_mov_b32 s10, s15

.LBB0_434:
	v_mov_b32_e32 v0, v142
	v_mov_b32_e32 v18, v142
	s_ashr_i32 s2, s7, 31
	v_lshlrev_b32_e32 v19, 4, v18
	v_bfe_i32 v3, v18, 27, 1
	s_waitcnt lgkmcnt(0)
	v_add_u32_e32 v21, 0x2000, v19
	v_lshrrev_b32_e32 v3, 22, v3
	v_ashrrev_i32_e32 v8, 31, v21
	v_add_u32_e32 v3, v19, v3
	v_lshrrev_b32_e32 v8, 22, v8
	s_lshr_b32 s2, s2, 27
	v_and_b32_e32 v3, 0xfffffc00, v3
	v_add_u32_e32 v8, v21, v8
	s_add_i32 s2, s7, s2
	v_ashrrev_i32_e32 v2, 31, v18
	v_sub_u32_e32 v3, v19, v3
	v_ashrrev_i32_e32 v8, 10, v8
	s_and_b32 s3, s2, 0xffffffe0
	v_lshrrev_b32_e32 v2, 26, v2
	v_lshrrev_b32_e32 v4, 4, v3
	v_mul_i32_i24_e32 v9, 0x400, v8
	s_sub_i32 s9, s7, s3
	v_add_u32_e32 v2, v18, v2
	v_bitop3_b32 v4, v4, v3, 32 bitop3:0x6c
	v_ashrrev_i32_e32 v3, 31, v3
	v_sub_u32_e32 v9, v21, v9
	s_lshl_b32 s2, s2, 2
	s_mul_i32 s11, s9, 0x108000
	v_ashrrev_i32_e32 v2, 6, v2
	v_lshrrev_b32_e32 v3, 26, v3
	v_lshrrev_b32_e32 v10, 4, v9
	s_and_b32 s8, s2, 0xffffff80
	s_ashr_i32 s14, s11, 31
	v_lshlrev_b32_e32 v5, 3, v2
	v_add_u32_e32 v3, v4, v3
	v_bitop3_b32 v9, v10, v9, 32 bitop3:0x6c
	s_add_u32 s12, s26, s11
	v_and_b32_e32 v5, -16, v5
	v_ashrrev_i32_e32 v3, 6, v3
	v_ashrrev_i32_e32 v11, 31, v9
	s_addc_u32 s13, s27, s14
	v_add_u32_e32 v20, v3, v5
	v_mul_i32_i24_e32 v3, 64, v3
	v_lshrrev_b32_e32 v11, 26, v11
	v_sub_u32_e32 v3, v4, v3
	v_mov_b64_e32 v[4:5], s[12:13]
	v_lshlrev_b32_e32 v10, 3, v8
	v_add_u32_e32 v11, v9, v11
	v_mad_i64_i32 v[6:7], s[12:13], v20, s67, v[4:5]
	v_add_u32_e32 v60, 0, v19
	v_and_b32_e32 v10, -16, v10
	v_ashrrev_i32_e32 v12, 6, v11
	v_readfirstlane_b32 s12, v60
	v_add_u32_e32 v22, v12, v10
	v_and_b32_e32 v10, 0xc0, v11
	s_mov_b32 m0, s12
	v_sub_u32_e32 v9, v9, v10
	v_mad_i64_i32 v[10:11], s[12:13], v22, s67, v[4:5]
	v_add_u32_e32 v12, 0x2000, v60
	v_add_u32_e32 v23, 0x4000, v19
	v_readfirstlane_b32 s12, v12
	v_ashrrev_i32_e32 v12, 31, v23
	v_lshrrev_b32_e32 v12, 22, v12
	v_add_u32_e32 v12, v23, v12
	v_ashrrev_i32_e32 v12, 10, v12
	v_mul_i32_i24_e32 v13, 0x400, v12
	v_sub_u32_e32 v13, v23, v13
	v_lshrrev_b32_e32 v14, 4, v13
	v_bitop3_b32 v13, v14, v13, 32 bitop3:0x6c
	v_ashrrev_i32_e32 v15, 31, v13
	v_lshlrev_b32_e32 v2, 5, v2
	v_lshrrev_b32_e32 v15, 26, v15
	v_and_b32_e32 v2, 32, v2
	v_ashrrev_i16_sdwa v3, v146, sext(v3) dst_sel:DWORD dst_unused:UNUSED_PAD src0_sel:DWORD src1_sel:BYTE_0
	v_lshlrev_b32_e32 v14, 3, v12
	v_add_u32_e32 v15, v13, v15
	v_add_u32_sdwa v2, v2, sext(v3) dst_sel:DWORD dst_unused:UNUSED_PAD src0_sel:DWORD src1_sel:WORD_0
	v_and_b32_e32 v14, -16, v14
	v_ashrrev_i32_e32 v16, 6, v15
	v_ashrrev_i32_e32 v3, 31, v2
	v_lshlrev_b32_e32 v8, 5, v8
	v_add_u32_e32 v24, v16, v14
	v_and_b32_e32 v14, 0xc0, v15
	s_mul_i32 s2, s8, 0x1600
	v_lshlrev_b64 v[2:3], 1, v[2:3]
	v_and_b32_e32 v8, 32, v8
	v_ashrrev_i16_sdwa v9, v146, sext(v9) dst_sel:DWORD dst_unused:UNUSED_PAD src0_sel:DWORD src1_sel:BYTE_0
	v_lshlrev_b32_e32 v12, 5, v12
	v_sub_u32_e32 v13, v13, v14
	s_mul_hi_i32 s3, s8, 0x1600
	s_add_u32 s2, s5, s2
	v_lshl_add_u64 v[6:7], v[6:7], 0, v[2:3]
	v_add_u32_sdwa v8, v8, sext(v9) dst_sel:DWORD dst_unused:UNUSED_PAD src0_sel:DWORD src1_sel:WORD_0
	v_and_b32_e32 v12, 32, v12
	v_ashrrev_i16_sdwa v13, v146, sext(v13) dst_sel:DWORD dst_unused:UNUSED_PAD src0_sel:DWORD src1_sel:BYTE_0
	s_addc_u32 s3, s6, s3
	s_waitcnt vmcnt(0)
	s_barrier
	v_ashrrev_i32_e32 v9, 31, v8
	s_mov_b32 m0, s12
	v_add_u32_sdwa v12, v12, sext(v13) dst_sel:DWORD dst_unused:UNUSED_PAD src0_sel:DWORD src1_sel:WORD_0
	v_mad_i64_i32 v[4:5], s[12:13], v24, s67, v[4:5]
	v_add_u32_e32 v14, 0x4000, v60
	v_lshlrev_b64 v[8:9], 1, v[8:9]
	v_ashrrev_i32_e32 v13, 31, v12
	v_readfirstlane_b32 s12, v14
	v_mov_b64_e32 v[14:15], s[2:3]
	v_lshl_add_u64 v[10:11], v[10:11], 0, v[8:9]
	v_lshlrev_b64 v[12:13], 1, v[12:13]
	v_mad_i64_i32 v[16:17], s[2:3], v20, s67, v[14:15]
	v_add_u32_e32 v25, 0x8000, v60
	v_lshl_add_u64 v[4:5], v[4:5], 0, v[12:13]
	s_mov_b32 m0, s12
	v_readfirstlane_b32 s2, v25
	s_mov_b32 m0, s2
	v_mad_i64_i32 v[14:15], s[2:3], v22, s67, v[14:15]
	v_add_u32_e32 v25, 0xa000, v60
	v_lshl_add_u64 v[16:17], v[16:17], 0, v[2:3]
	v_readfirstlane_b32 s2, v25
	v_add_u32_e32 v25, 0xc000, v60
	v_lshl_add_u64 v[14:15], v[14:15], 0, v[8:9]
	s_mov_b32 m0, s2
	v_readfirstlane_b32 s2, v25
	v_lshl_add_u64 v[6:7], v[6:7], 0, s[30:31]
	s_mov_b32 m0, s2
	v_lshl_add_u64 v[4:5], v[4:5], 0, s[30:31]
	v_lshl_add_u64 v[6:7], v[10:11], 0, s[30:31]
	v_add_u32_e32 v10, 0xe000, v60
	s_mov_b32 s10, 2
	v_readfirstlane_b32 s2, v10
	s_mov_b32 m0, s2
	s_add_i32 s2, 0, 0xc000
	v_add_u32_e32 v6, s2, v23
	v_lshlrev_b32_e32 v7, 2, v18
	v_readfirstlane_b32 s2, v6
	v_add_u32_e32 v6, s54, v19
	s_mov_b32 m0, s2
	v_readfirstlane_b32 s2, v6
	v_add_u32_e32 v6, s54, v21
	v_lshl_add_u64 v[4:5], v[16:17], 0, s[30:31]
	s_mov_b32 m0, s2
	v_readfirstlane_b32 s2, v6
	v_lshl_add_u64 v[4:5], v[14:15], 0, s[30:31]
	s_mov_b32 m0, s2
	v_and_b32_e32 v6, 48, v18
	v_lshlrev_b32_e32 v5, 6, v18
	v_and_b32_e32 v5, 0x3c0, v5
	v_and_b32_e32 v7, 32, v7
	v_lshrrev_b32_e32 v4, 7, v18
	v_bitop3_b32 v5, v5, v7, v6 bitop3:0x36
	v_lshlrev_b32_e32 v6, 7, v18
	s_movk_i32 s2, 0x1800
	v_and_b32_e32 v6, 0x2000, v6
	v_mul_lo_u32 v4, v4, s2
	s_add_i32 s2, 0, 0x8000
	v_add3_u32 v61, v4, 0, v5
	v_add3_u32 v62, v6, s2, v5
	v_mad_i64_i32 v[4:5], s[2:3], v22, s67, 0
	v_mad_i64_i32 v[4:5], s[2:3], s8, v157, v[4:5]
	v_lshl_add_u64 v[4:5], v[4:5], 0, v[8:9]
	v_lshl_add_u64 v[50:51], s[0:1], 0, v[4:5]
	v_mad_i64_i32 v[4:5], s[2:3], v20, s67, 0
	v_mad_i64_i32 v[4:5], s[2:3], s8, v157, v[4:5]
	v_lshl_add_u64 v[4:5], v[4:5], 0, v[2:3]
	v_lshl_add_u64 v[52:53], s[0:1], 0, v[4:5]
	v_mad_i64_i32 v[4:5], s[2:3], v24, s67, v[12:13]
	v_readlane_b32 s2, v214, 32
	s_add_u32 s2, s2, s11
	v_readlane_b32 s3, v214, 33
	s_addc_u32 s3, s3, s14
	v_mad_i64_i32 v[2:3], s[12:13], v20, s67, v[2:3]
	v_lshl_add_u64 v[54:55], s[2:3], 0, v[4:5]
	v_mad_i64_i32 v[4:5], s[12:13], v22, s67, v[8:9]
	v_lshl_add_u64 v[58:59], s[2:3], 0, v[2:3]
	v_mov_b32_e32 v2, 0
	v_lshl_add_u64 v[56:57], s[2:3], 0, v[4:5]
	s_mov_b32 s11, 0
	s_mov_b64 s[2:3], 0
	v_mov_b32_e32 v3, v2
	v_mov_b32_e32 v4, v2
	v_mov_b32_e32 v5, v2
	v_mov_b32_e32 v6, v2
	v_mov_b32_e32 v7, v2
	v_mov_b32_e32 v8, v2
	v_mov_b32_e32 v9, v2
	v_mov_b32_e32 v10, v2
	v_mov_b32_e32 v11, v2
	v_mov_b32_e32 v12, v2
	v_mov_b32_e32 v13, v2
	v_mov_b32_e32 v14, v2
	v_mov_b32_e32 v15, v2
	v_mov_b32_e32 v16, v2
	v_mov_b32_e32 v17, v2
	v_mov_b32_e32 v18, v2
	v_mov_b32_e32 v19, v2
	v_mov_b32_e32 v20, v2
	v_mov_b32_e32 v21, v2
	v_mov_b32_e32 v22, v2
	v_mov_b32_e32 v23, v2
	v_mov_b32_e32 v24, v2
	v_mov_b32_e32 v25, v2
	v_mov_b32_e32 v26, v2
	v_mov_b32_e32 v27, v2
	v_mov_b32_e32 v28, v2
	v_mov_b32_e32 v29, v2
	v_mov_b32_e32 v30, v2
	v_mov_b32_e32 v31, v2
	v_mov_b32_e32 v32, v2
	v_mov_b32_e32 v33, v2
	v_mov_b32_e32 v34, v2
	v_mov_b32_e32 v35, v2
	v_mov_b32_e32 v36, v2
	v_mov_b32_e32 v37, v2
	v_mov_b32_e32 v38, v2
	v_mov_b32_e32 v39, v2
	v_mov_b32_e32 v40, v2
	v_mov_b32_e32 v41, v2
	v_mov_b32_e32 v42, v2
	v_mov_b32_e32 v43, v2
	v_mov_b32_e32 v44, v2
	v_mov_b32_e32 v45, v2
	v_mov_b32_e32 v46, v2
	v_mov_b32_e32 v47, v2
	v_mov_b32_e32 v48, v2
	v_mov_b32_e32 v49, v2
.LBB0_435:
	v_readlane_b32 s42, v214, 57
	s_and_b32 s43, s7, 31
	s_mul_i32 s43, s43, 0x108000
	s_add_u32 s38, s26, s43
	s_addc_u32 s39, s27, 0
	s_mul_hi_u32 s12, s42, 0x3500000
	s_mul_i32 s42, s42, 0x3500000
	s_add_u32 s40, s48, s42
	s_addc_u32 s41, s49, s12
	s_add_u32 s40, s40, 0x1254e000
	s_addc_u32 s41, s41, 0
	s_lshr_b32 s43, s7, 5
	s_mul_i32 s43, s43, 0xb0000
	s_add_u32 s40, s40, s43
	s_addc_u32 s41, s41, 0
	v_and_b32_e32 v226, 63, v142
	v_lshlrev_b32_e32 v222, 4, v226
	v_lshrrev_b32_e32 v227, 5, v226
	v_lshlrev_b32_e32 v227, 5, v227
	v_xor_b32_e32 v222, v222, v227
	v_lshrrev_b32_e32 v226, 6, v142
	v_and_b32_e32 v227, 1, v226
	v_lshrrev_b32_e32 v226, 1, v226
	v_lshl_add_u32 v222, v227, 10, v222
	v_mul_u32_u24_e32 v226, 0x16000, v226
	v_add_u32_e32 v222, v222, v226
	v_add_u32_e32 v223, 0x58000, v222
	v_add_u32_e32 v224, 0x58000, v223
	v_add_u32_e32 v218, 0x0, v60
	s_nop 0
	v_readfirstlane_b32 s12, v218
	s_add_u32 m0, s12, 0x0
	s_nop 0
	global_load_lds_dwordx4 v222, s[38:39]
	s_add_u32 m0, s12, 0x2000
	s_nop 0
	global_load_lds_dwordx4 v223, s[38:39]
	s_add_u32 m0, s12, 0x4000
	s_nop 0
	global_load_lds_dwordx4 v224, s[38:39]
	s_add_u32 m0, s12, 0x8000
	s_nop 0
	global_load_lds_dwordx4 v222, s[40:41]
	s_add_u32 m0, s12, 0xa000
	s_nop 0
	global_load_lds_dwordx4 v223, s[40:41]
	s_add_u32 s38, s38, 0x800
	s_addc_u32 s39, s39, 0
	s_add_u32 s40, s40, 0x800
	s_addc_u32 s41, s41, 0
	v_add_u32_e32 v218, 0xc000, v60
	s_nop 0
	v_readfirstlane_b32 s12, v218
	s_add_u32 m0, s12, 0x0
	s_nop 0
	global_load_lds_dwordx4 v222, s[38:39]
	s_add_u32 m0, s12, 0x2000
	s_nop 0
	global_load_lds_dwordx4 v223, s[38:39]
	s_add_u32 m0, s12, 0x4000
	s_nop 0
	global_load_lds_dwordx4 v224, s[38:39]
	s_add_u32 m0, s12, 0x8000
	s_nop 0
	global_load_lds_dwordx4 v222, s[40:41]
	s_add_u32 m0, s12, 0xa000
	s_nop 0
	global_load_lds_dwordx4 v223, s[40:41]
	s_add_u32 s38, s38, 0x800
	s_addc_u32 s39, s39, 0
	s_add_u32 s40, s40, 0x800
	s_addc_u32 s41, s41, 0
	s_mov_b32 s42, 42
.Lgb_dn1:
	s_waitcnt vmcnt(5)
	s_barrier
	s_mul_i32 s12, s11, 0xc000
	v_add_u32_e32 v220, s12, v61
	v_add_u32_e32 v221, s12, v62
	ds_read_b128 v[64:67], v220 offset:0
	ds_read_b128 v[68:71], v220 offset:2048
	ds_read_b128 v[72:75], v220 offset:4096
	ds_read_b128 v[76:79], v221 offset:0
	ds_read_b128 v[80:83], v221 offset:2048
	ds_read_b128 v[84:87], v221 offset:4096
	ds_read_b128 v[88:91], v221 offset:6144
	s_mul_i32 s12, s10, 0xc000
	v_add_u32_e32 v218, s12, v60
	s_nop 0
	v_readfirstlane_b32 s12, v218
	s_add_u32 m0, s12, 0x0
	s_nop 0
	global_load_lds_dwordx4 v222, s[38:39]
	s_add_u32 m0, s12, 0x2000
	s_nop 0
	global_load_lds_dwordx4 v223, s[38:39]
	s_add_u32 m0, s12, 0x4000
	s_nop 0
	global_load_lds_dwordx4 v224, s[38:39]
	s_add_u32 m0, s12, 0x8000
	s_nop 0
	global_load_lds_dwordx4 v222, s[40:41]
	s_add_u32 m0, s12, 0xa000
	s_nop 0
	global_load_lds_dwordx4 v223, s[40:41]
	ds_read_b128 v[92:95], v220 offset:1024
	ds_read_b128 v[96:99], v220 offset:3072
	ds_read_b128 v[100:103], v220 offset:5120
	ds_read_b128 v[104:107], v221 offset:1024
	ds_read_b128 v[108:111], v221 offset:3072
	ds_read_b128 v[112:115], v221 offset:5120
	ds_read_b128 v[116:119], v221 offset:7168
	s_waitcnt lgkmcnt(7)
	v_mfma_f32_16x16x32_bf16 v[46:49], v[76:79], v[64:67], v[46:49]
	v_mfma_f32_16x16x32_bf16 v[42:45], v[80:83], v[64:67], v[42:45]
	v_mfma_f32_16x16x32_bf16 v[38:41], v[84:87], v[64:67], v[38:41]
	v_mfma_f32_16x16x32_bf16 v[34:37], v[88:91], v[64:67], v[34:37]
	v_mfma_f32_16x16x32_bf16 v[30:33], v[76:79], v[68:71], v[30:33]
	v_mfma_f32_16x16x32_bf16 v[26:29], v[80:83], v[68:71], v[26:29]
	v_mfma_f32_16x16x32_bf16 v[22:25], v[84:87], v[68:71], v[22:25]
	v_mfma_f32_16x16x32_bf16 v[18:21], v[88:91], v[68:71], v[18:21]
	v_mfma_f32_16x16x32_bf16 v[14:17], v[76:79], v[72:75], v[14:17]
	v_mfma_f32_16x16x32_bf16 v[10:13], v[80:83], v[72:75], v[10:13]
	v_mfma_f32_16x16x32_bf16 v[6:9], v[84:87], v[72:75], v[6:9]
	v_mfma_f32_16x16x32_bf16 v[2:5], v[88:91], v[72:75], v[2:5]
	s_waitcnt lgkmcnt(0)
	s_add_i32 s12, s11, 1
	s_cmp_lg_u32 s11, 2
	s_cselect_b32 s11, s12, 0
	s_add_i32 s12, s10, 1
	s_cmp_lg_u32 s10, 2
	s_cselect_b32 s10, s12, 0
	s_add_u32 s38, s38, 0x800
	s_addc_u32 s39, s39, 0
	s_add_u32 s40, s40, 0x800
	s_addc_u32 s41, s41, 0
	s_sub_u32 s42, s42, 1
.Lgbl_dn1:
	s_waitcnt vmcnt(5)
	s_barrier
	s_mul_i32 s12, s11, 0xc000
	v_add_u32_e32 v220, s12, v61
	v_add_u32_e32 v221, s12, v62
	ds_read_b128 v[64:67], v220 offset:0
	ds_read_b128 v[68:71], v220 offset:2048
	ds_read_b128 v[72:75], v220 offset:4096
	ds_read_b128 v[76:79], v221 offset:0
	ds_read_b128 v[80:83], v221 offset:2048
	ds_read_b128 v[84:87], v221 offset:4096
	ds_read_b128 v[88:91], v221 offset:6144
	s_mul_i32 s12, s10, 0xc000
	v_add_u32_e32 v218, s12, v60
	s_nop 0
	v_readfirstlane_b32 s12, v218
	v_mfma_f32_16x16x32_bf16 v[46:49], v[104:107], v[92:95], v[46:49]
	v_mfma_f32_16x16x32_bf16 v[42:45], v[108:111], v[92:95], v[42:45]
	s_add_u32 m0, s12, 0x0
	s_nop 0
	global_load_lds_dwordx4 v222, s[38:39]
	v_mfma_f32_16x16x32_bf16 v[38:41], v[112:115], v[92:95], v[38:41]
	v_mfma_f32_16x16x32_bf16 v[34:37], v[116:119], v[92:95], v[34:37]
	s_add_u32 m0, s12, 0x2000
	s_nop 0
	global_load_lds_dwordx4 v223, s[38:39]
	v_mfma_f32_16x16x32_bf16 v[30:33], v[104:107], v[96:99], v[30:33]
	v_mfma_f32_16x16x32_bf16 v[26:29], v[108:111], v[96:99], v[26:29]
	s_add_u32 m0, s12, 0x4000
	s_nop 0
	global_load_lds_dwordx4 v224, s[38:39]
	v_mfma_f32_16x16x32_bf16 v[22:25], v[112:115], v[96:99], v[22:25]
	v_mfma_f32_16x16x32_bf16 v[18:21], v[116:119], v[96:99], v[18:21]
	s_add_u32 m0, s12, 0x8000
	s_nop 0
	global_load_lds_dwordx4 v222, s[40:41]
	v_mfma_f32_16x16x32_bf16 v[14:17], v[104:107], v[100:103], v[14:17]
	v_mfma_f32_16x16x32_bf16 v[10:13], v[108:111], v[100:103], v[10:13]
	s_add_u32 m0, s12, 0xa000
	s_nop 0
	global_load_lds_dwordx4 v223, s[40:41]
	v_mfma_f32_16x16x32_bf16 v[6:9], v[112:115], v[100:103], v[6:9]
	v_mfma_f32_16x16x32_bf16 v[2:5], v[116:119], v[100:103], v[2:5]
	ds_read_b128 v[92:95], v220 offset:1024
	ds_read_b128 v[96:99], v220 offset:3072
	ds_read_b128 v[100:103], v220 offset:5120
	ds_read_b128 v[104:107], v221 offset:1024
	ds_read_b128 v[108:111], v221 offset:3072
	ds_read_b128 v[112:115], v221 offset:5120
	ds_read_b128 v[116:119], v221 offset:7168
	s_waitcnt lgkmcnt(7)
	v_mfma_f32_16x16x32_bf16 v[46:49], v[76:79], v[64:67], v[46:49]
	v_mfma_f32_16x16x32_bf16 v[42:45], v[80:83], v[64:67], v[42:45]
	v_mfma_f32_16x16x32_bf16 v[38:41], v[84:87], v[64:67], v[38:41]
	v_mfma_f32_16x16x32_bf16 v[34:37], v[88:91], v[64:67], v[34:37]
	v_mfma_f32_16x16x32_bf16 v[30:33], v[76:79], v[68:71], v[30:33]
	v_mfma_f32_16x16x32_bf16 v[26:29], v[80:83], v[68:71], v[26:29]
	v_mfma_f32_16x16x32_bf16 v[22:25], v[84:87], v[68:71], v[22:25]
	v_mfma_f32_16x16x32_bf16 v[18:21], v[88:91], v[68:71], v[18:21]
	v_mfma_f32_16x16x32_bf16 v[14:17], v[76:79], v[72:75], v[14:17]
	v_mfma_f32_16x16x32_bf16 v[10:13], v[80:83], v[72:75], v[10:13]
	v_mfma_f32_16x16x32_bf16 v[6:9], v[84:87], v[72:75], v[6:9]
	v_mfma_f32_16x16x32_bf16 v[2:5], v[88:91], v[72:75], v[2:5]
	s_waitcnt lgkmcnt(0)
	s_add_i32 s12, s11, 1
	s_cmp_lg_u32 s11, 2
	s_cselect_b32 s11, s12, 0
	s_add_i32 s12, s10, 1
	s_cmp_lg_u32 s10, 2
	s_cselect_b32 s10, s12, 0
	s_add_u32 s38, s38, 0x800
	s_addc_u32 s39, s39, 0
	s_add_u32 s40, s40, 0x800
	s_addc_u32 s41, s41, 0
	s_sub_u32 s42, s42, 1
	s_cmp_lg_u32 s42, 0
	s_cbranch_scc1 .Lgbl_dn1
	s_waitcnt vmcnt(5)
	s_barrier
	s_mul_i32 s12, s11, 0xc000
	v_add_u32_e32 v220, s12, v61
	v_add_u32_e32 v221, s12, v62
	ds_read_b128 v[64:67], v220 offset:0
	ds_read_b128 v[68:71], v220 offset:2048
	ds_read_b128 v[72:75], v220 offset:4096
	ds_read_b128 v[76:79], v221 offset:0
	ds_read_b128 v[80:83], v221 offset:2048
	ds_read_b128 v[84:87], v221 offset:4096
	ds_read_b128 v[88:91], v221 offset:6144
	v_mfma_f32_16x16x32_bf16 v[46:49], v[104:107], v[92:95], v[46:49]
	v_mfma_f32_16x16x32_bf16 v[42:45], v[108:111], v[92:95], v[42:45]
	v_mfma_f32_16x16x32_bf16 v[38:41], v[112:115], v[92:95], v[38:41]
	v_mfma_f32_16x16x32_bf16 v[34:37], v[116:119], v[92:95], v[34:37]
	v_mfma_f32_16x16x32_bf16 v[30:33], v[104:107], v[96:99], v[30:33]
	v_mfma_f32_16x16x32_bf16 v[26:29], v[108:111], v[96:99], v[26:29]
	v_mfma_f32_16x16x32_bf16 v[22:25], v[112:115], v[96:99], v[22:25]
	v_mfma_f32_16x16x32_bf16 v[18:21], v[116:119], v[96:99], v[18:21]
	v_mfma_f32_16x16x32_bf16 v[14:17], v[104:107], v[100:103], v[14:17]
	v_mfma_f32_16x16x32_bf16 v[10:13], v[108:111], v[100:103], v[10:13]
	v_mfma_f32_16x16x32_bf16 v[6:9], v[112:115], v[100:103], v[6:9]
	v_mfma_f32_16x16x32_bf16 v[2:5], v[116:119], v[100:103], v[2:5]
	ds_read_b128 v[92:95], v220 offset:1024
	ds_read_b128 v[96:99], v220 offset:3072
	ds_read_b128 v[100:103], v220 offset:5120
	ds_read_b128 v[104:107], v221 offset:1024
	ds_read_b128 v[108:111], v221 offset:3072
	ds_read_b128 v[112:115], v221 offset:5120
	ds_read_b128 v[116:119], v221 offset:7168
	s_waitcnt lgkmcnt(7)
	v_mfma_f32_16x16x32_bf16 v[46:49], v[76:79], v[64:67], v[46:49]
	v_mfma_f32_16x16x32_bf16 v[42:45], v[80:83], v[64:67], v[42:45]
	v_mfma_f32_16x16x32_bf16 v[38:41], v[84:87], v[64:67], v[38:41]
	v_mfma_f32_16x16x32_bf16 v[34:37], v[88:91], v[64:67], v[34:37]
	v_mfma_f32_16x16x32_bf16 v[30:33], v[76:79], v[68:71], v[30:33]
	v_mfma_f32_16x16x32_bf16 v[26:29], v[80:83], v[68:71], v[26:29]
	v_mfma_f32_16x16x32_bf16 v[22:25], v[84:87], v[68:71], v[22:25]
	v_mfma_f32_16x16x32_bf16 v[18:21], v[88:91], v[68:71], v[18:21]
	v_mfma_f32_16x16x32_bf16 v[14:17], v[76:79], v[72:75], v[14:17]
	v_mfma_f32_16x16x32_bf16 v[10:13], v[80:83], v[72:75], v[10:13]
	v_mfma_f32_16x16x32_bf16 v[6:9], v[84:87], v[72:75], v[6:9]
	v_mfma_f32_16x16x32_bf16 v[2:5], v[88:91], v[72:75], v[2:5]
	s_waitcnt lgkmcnt(0)
	s_add_i32 s12, s11, 1
	s_cmp_lg_u32 s11, 2
	s_cselect_b32 s11, s12, 0
	s_add_i32 s12, s10, 1
	s_cmp_lg_u32 s10, 2
	s_cselect_b32 s10, s12, 0
	s_waitcnt vmcnt(0)
	s_barrier
	s_mul_i32 s12, s11, 0xc000
	v_add_u32_e32 v220, s12, v61
	v_add_u32_e32 v221, s12, v62
	ds_read_b128 v[64:67], v220 offset:0
	ds_read_b128 v[68:71], v220 offset:2048
	ds_read_b128 v[72:75], v220 offset:4096
	ds_read_b128 v[76:79], v221 offset:0
	ds_read_b128 v[80:83], v221 offset:2048
	ds_read_b128 v[84:87], v221 offset:4096
	ds_read_b128 v[88:91], v221 offset:6144
	v_mfma_f32_16x16x32_bf16 v[46:49], v[104:107], v[92:95], v[46:49]
	v_mfma_f32_16x16x32_bf16 v[42:45], v[108:111], v[92:95], v[42:45]
	v_mfma_f32_16x16x32_bf16 v[38:41], v[112:115], v[92:95], v[38:41]
	v_mfma_f32_16x16x32_bf16 v[34:37], v[116:119], v[92:95], v[34:37]
	v_mfma_f32_16x16x32_bf16 v[30:33], v[104:107], v[96:99], v[30:33]
	v_mfma_f32_16x16x32_bf16 v[26:29], v[108:111], v[96:99], v[26:29]
	v_mfma_f32_16x16x32_bf16 v[22:25], v[112:115], v[96:99], v[22:25]
	v_mfma_f32_16x16x32_bf16 v[18:21], v[116:119], v[96:99], v[18:21]
	v_mfma_f32_16x16x32_bf16 v[14:17], v[104:107], v[100:103], v[14:17]
	v_mfma_f32_16x16x32_bf16 v[10:13], v[108:111], v[100:103], v[10:13]
	v_mfma_f32_16x16x32_bf16 v[6:9], v[112:115], v[100:103], v[6:9]
	v_mfma_f32_16x16x32_bf16 v[2:5], v[116:119], v[100:103], v[2:5]
	ds_read_b128 v[92:95], v220 offset:1024
	ds_read_b128 v[96:99], v220 offset:3072
	ds_read_b128 v[100:103], v220 offset:5120
	ds_read_b128 v[104:107], v221 offset:1024
	ds_read_b128 v[108:111], v221 offset:3072
	ds_read_b128 v[112:115], v221 offset:5120
	ds_read_b128 v[116:119], v221 offset:7168
	s_waitcnt lgkmcnt(7)
	v_mfma_f32_16x16x32_bf16 v[46:49], v[76:79], v[64:67], v[46:49]
	v_mfma_f32_16x16x32_bf16 v[42:45], v[80:83], v[64:67], v[42:45]
	v_mfma_f32_16x16x32_bf16 v[38:41], v[84:87], v[64:67], v[38:41]
	v_mfma_f32_16x16x32_bf16 v[34:37], v[88:91], v[64:67], v[34:37]
	v_mfma_f32_16x16x32_bf16 v[30:33], v[76:79], v[68:71], v[30:33]
	v_mfma_f32_16x16x32_bf16 v[26:29], v[80:83], v[68:71], v[26:29]
	v_mfma_f32_16x16x32_bf16 v[22:25], v[84:87], v[68:71], v[22:25]
	v_mfma_f32_16x16x32_bf16 v[18:21], v[88:91], v[68:71], v[18:21]
	v_mfma_f32_16x16x32_bf16 v[14:17], v[76:79], v[72:75], v[14:17]
	v_mfma_f32_16x16x32_bf16 v[10:13], v[80:83], v[72:75], v[10:13]
	v_mfma_f32_16x16x32_bf16 v[6:9], v[84:87], v[72:75], v[6:9]
	v_mfma_f32_16x16x32_bf16 v[2:5], v[88:91], v[72:75], v[2:5]
	s_waitcnt lgkmcnt(0)
	s_add_i32 s12, s11, 1
	s_cmp_lg_u32 s11, 2
	s_cselect_b32 s11, s12, 0
	s_add_i32 s12, s10, 1
	s_cmp_lg_u32 s10, 2
	s_cselect_b32 s10, s12, 0
	v_mfma_f32_16x16x32_bf16 v[46:49], v[104:107], v[92:95], v[46:49]
	v_mfma_f32_16x16x32_bf16 v[42:45], v[108:111], v[92:95], v[42:45]
	v_mfma_f32_16x16x32_bf16 v[38:41], v[112:115], v[92:95], v[38:41]
	v_mfma_f32_16x16x32_bf16 v[34:37], v[116:119], v[92:95], v[34:37]
	v_mfma_f32_16x16x32_bf16 v[30:33], v[104:107], v[96:99], v[30:33]
	v_mfma_f32_16x16x32_bf16 v[26:29], v[108:111], v[96:99], v[26:29]
	v_mfma_f32_16x16x32_bf16 v[22:25], v[112:115], v[96:99], v[22:25]
	v_mfma_f32_16x16x32_bf16 v[18:21], v[116:119], v[96:99], v[18:21]
	v_mfma_f32_16x16x32_bf16 v[14:17], v[104:107], v[100:103], v[14:17]
	v_mfma_f32_16x16x32_bf16 v[10:13], v[108:111], v[100:103], v[10:13]
	v_mfma_f32_16x16x32_bf16 v[6:9], v[112:115], v[100:103], v[6:9]
	v_mfma_f32_16x16x32_bf16 v[2:5], v[116:119], v[100:103], v[2:5]
.Lgd_dn1:
	s_nop 7
	s_nop 1
	v_mov_b32_e32 v50, v38
	v_mov_b32_e32 v51, v39
	v_mov_b32_e32 v52, v40
	v_mov_b32_e32 v53, v41
	v_mov_b32_e32 v54, v34
	v_mov_b32_e32 v55, v35
	v_mov_b32_e32 v56, v36
	v_mov_b32_e32 v57, v37
	s_mulk_i32 s9, 0xc0
	v_and_b32_e32 v112, 64, v0
	v_ashrrev_i32_e32 v106, 7, v0
	s_nop 7
	v_readlane_b32 s68, v214, 57
	s_and_b32 s2, s7, 31
	s_mul_i32 s2, s2, 192
	s_lshr_b32 s3, s7, 5
	s_lshl_b32 s3, s3, 7
	s_mul_i32 s10, s68, 0x1b000
	s_add_u32 s10, s10, 0x8000
	s_add_u32 s38, s34, s10
	s_addc_u32 s39, s35, 0
	v_lshrrev_b32_e32 v128, 6, v142
	v_and_b32_e32 v129, 1, v128
	v_lshrrev_b32_e32 v128, 1, v128
	v_lshlrev_b32_e32 v66, 6, v129
	v_lshrrev_b32_e32 v129, 4, v142
	v_and_b32_e32 v129, 3, v129
	v_lshl_add_u32 v66, v129, 2, v66
	v_add_u32_e32 v66, s3, v66
	v_lshlrev_b32_e32 v66, 2, v66
	v_mul_u32_u24_e32 v67, 48, v128
	v_and_b32_e32 v129, 15, v142
	v_add3_u32 v67, v67, v129, s2
	v_add_u32_e32 v128, 0, v67
	v_lshl_add_u32 v141, v128, 12, v66
	v_add_u32_e32 v129, 0xfffff000, v128
	v_lshrrev_b32_e32 v129, 10, v129
	v_add_u32_e32 v129, 1, v129
	v_cmp_gt_u32_e32 vcc, 0x1000, v128
	v_cndmask_b32_e64 v129, v129, 0, vcc
	v_mul_u32_u24_e32 v129, 0x9000, v129
	v_add_u32_e32 v134, v129, v66
	global_load_dwordx4 v[68:71], v134, s[38:39] offset:0
	global_load_dwordx4 v[72:75], v134, s[38:39] offset:64
	global_load_dwordx4 v[76:79], v134, s[38:39] offset:128
	global_load_dwordx4 v[80:83], v134, s[38:39] offset:192
	v_add_u32_e32 v128, 16, v67
	v_lshl_add_u32 v162, v128, 12, v66
	v_add_u32_e32 v129, 0xfffff000, v128
	v_lshrrev_b32_e32 v129, 10, v129
	v_add_u32_e32 v129, 1, v129
	v_cmp_gt_u32_e32 vcc, 0x1000, v128
	v_cndmask_b32_e64 v129, v129, 0, vcc
	v_mul_u32_u24_e32 v129, 0x9000, v129
	v_add_u32_e32 v135, v129, v66
	global_load_dwordx4 v[84:87], v135, s[38:39] offset:0
	global_load_dwordx4 v[88:91], v135, s[38:39] offset:64
	global_load_dwordx4 v[92:95], v135, s[38:39] offset:128
	global_load_dwordx4 v[96:99], v135, s[38:39] offset:192
	v_add_u32_e32 v128, 32, v67
	v_lshl_add_u32 v163, v128, 12, v66
	v_add_u32_e32 v129, 0xfffff000, v128
	v_lshrrev_b32_e32 v129, 10, v129
	v_add_u32_e32 v129, 1, v129
	v_cmp_gt_u32_e32 vcc, 0x1000, v128
	v_cndmask_b32_e64 v129, v129, 0, vcc
	v_mul_u32_u24_e32 v129, 0x9000, v129
	v_add_u32_e32 v140, v129, v66
	global_load_dwordx4 v[100:103], v140, s[38:39] offset:0
	global_load_dwordx4 v[104:107], v140, s[38:39] offset:64
	global_load_dwordx4 v[108:111], v140, s[38:39] offset:128
	global_load_dwordx4 v[112:115], v140, s[38:39] offset:192
	global_load_dwordx4 v[116:119], v141, s[48:49] offset:0
	global_load_dwordx4 v[120:123], v141, s[48:49] offset:64
	global_load_dwordx4 v[124:127], v141, s[48:49] offset:128
	global_load_dwordx4 v[136:139], v141, s[48:49] offset:192
	global_load_dwordx4 v[164:167], v162, s[48:49] offset:0
	global_load_dwordx4 v[168:171], v162, s[48:49] offset:64
	global_load_dwordx4 v[172:175], v162, s[48:49] offset:128
	global_load_dwordx4 v[176:179], v162, s[48:49] offset:192
	global_load_dwordx4 v[180:183], v163, s[48:49] offset:0
	global_load_dwordx4 v[184:187], v163, s[48:49] offset:64
	global_load_dwordx4 v[188:191], v163, s[48:49] offset:128
	global_load_dwordx4 v[192:195], v163, s[48:49] offset:192
	s_waitcnt vmcnt(0)
	v_mul_f32_e32 v68, 0.5, v68
	v_mul_f32_e32 v69, 0.5, v69
	v_mul_f32_e32 v70, 0.5, v70
	v_mul_f32_e32 v71, 0.5, v71
	v_fma_f32 v116, v46, v68, v116
	v_fma_f32 v117, v47, v69, v117
	v_fma_f32 v118, v48, v70, v118
	v_fma_f32 v119, v49, v71, v119
	global_store_dwordx4 v141, v[116:119], s[48:49] offset:0
	v_mul_f32_e32 v72, 0.5, v72
	v_mul_f32_e32 v73, 0.5, v73
	v_mul_f32_e32 v74, 0.5, v74
	v_mul_f32_e32 v75, 0.5, v75
	v_fma_f32 v120, v42, v72, v120
	v_fma_f32 v121, v43, v73, v121
	v_fma_f32 v122, v44, v74, v122
	v_fma_f32 v123, v45, v75, v123
	global_store_dwordx4 v141, v[120:123], s[48:49] offset:64
	v_mul_f32_e32 v76, 0.5, v76
	v_mul_f32_e32 v77, 0.5, v77
	v_mul_f32_e32 v78, 0.5, v78
	v_mul_f32_e32 v79, 0.5, v79
	v_fma_f32 v124, v50, v76, v124
	v_fma_f32 v125, v51, v77, v125
	v_fma_f32 v126, v52, v78, v126
	v_fma_f32 v127, v53, v79, v127
	global_store_dwordx4 v141, v[124:127], s[48:49] offset:128
	v_mul_f32_e32 v80, 0.5, v80
	v_mul_f32_e32 v81, 0.5, v81
	v_mul_f32_e32 v82, 0.5, v82
	v_mul_f32_e32 v83, 0.5, v83
	v_fma_f32 v136, v54, v80, v136
	v_fma_f32 v137, v55, v81, v137
	v_fma_f32 v138, v56, v82, v138
	v_fma_f32 v139, v57, v83, v139
	global_store_dwordx4 v141, v[136:139], s[48:49] offset:192
	v_mul_f32_e32 v84, 0.5, v84
	v_mul_f32_e32 v85, 0.5, v85
	v_mul_f32_e32 v86, 0.5, v86
	v_mul_f32_e32 v87, 0.5, v87
	v_fma_f32 v164, v30, v84, v164
	v_fma_f32 v165, v31, v85, v165
	v_fma_f32 v166, v32, v86, v166
	v_fma_f32 v167, v33, v87, v167
	global_store_dwordx4 v162, v[164:167], s[48:49] offset:0
	v_mul_f32_e32 v88, 0.5, v88
	v_mul_f32_e32 v89, 0.5, v89
	v_mul_f32_e32 v90, 0.5, v90
	v_mul_f32_e32 v91, 0.5, v91
	v_fma_f32 v168, v26, v88, v168
	v_fma_f32 v169, v27, v89, v169
	v_fma_f32 v170, v28, v90, v170
	v_fma_f32 v171, v29, v91, v171
	global_store_dwordx4 v162, v[168:171], s[48:49] offset:64
	v_mul_f32_e32 v92, 0.5, v92
	v_mul_f32_e32 v93, 0.5, v93
	v_mul_f32_e32 v94, 0.5, v94
	v_mul_f32_e32 v95, 0.5, v95
	v_fma_f32 v172, v22, v92, v172
	v_fma_f32 v173, v23, v93, v173
	v_fma_f32 v174, v24, v94, v174
	v_fma_f32 v175, v25, v95, v175
	global_store_dwordx4 v162, v[172:175], s[48:49] offset:128
	v_mul_f32_e32 v96, 0.5, v96
	v_mul_f32_e32 v97, 0.5, v97
	v_mul_f32_e32 v98, 0.5, v98
	v_mul_f32_e32 v99, 0.5, v99
	v_fma_f32 v176, v18, v96, v176
	v_fma_f32 v177, v19, v97, v177
	v_fma_f32 v178, v20, v98, v178
	v_fma_f32 v179, v21, v99, v179
	global_store_dwordx4 v162, v[176:179], s[48:49] offset:192
	v_mul_f32_e32 v100, 0.5, v100
	v_mul_f32_e32 v101, 0.5, v101
	v_mul_f32_e32 v102, 0.5, v102
	v_mul_f32_e32 v103, 0.5, v103
	v_fma_f32 v180, v14, v100, v180
	v_fma_f32 v181, v15, v101, v181
	v_fma_f32 v182, v16, v102, v182
	v_fma_f32 v183, v17, v103, v183
	global_store_dwordx4 v163, v[180:183], s[48:49] offset:0
	v_mul_f32_e32 v104, 0.5, v104
	v_mul_f32_e32 v105, 0.5, v105
	v_mul_f32_e32 v106, 0.5, v106
	v_mul_f32_e32 v107, 0.5, v107
	v_fma_f32 v184, v10, v104, v184
	v_fma_f32 v185, v11, v105, v185
	v_fma_f32 v186, v12, v106, v186
	v_fma_f32 v187, v13, v107, v187
	global_store_dwordx4 v163, v[184:187], s[48:49] offset:64
	v_mul_f32_e32 v108, 0.5, v108
	v_mul_f32_e32 v109, 0.5, v109
	v_mul_f32_e32 v110, 0.5, v110
	v_mul_f32_e32 v111, 0.5, v111
	v_fma_f32 v188, v6, v108, v188
	v_fma_f32 v189, v7, v109, v189
	v_fma_f32 v190, v8, v110, v190
	v_fma_f32 v191, v9, v111, v191
	global_store_dwordx4 v163, v[188:191], s[48:49] offset:128
	v_mul_f32_e32 v112, 0.5, v112
	v_mul_f32_e32 v113, 0.5, v113
	v_mul_f32_e32 v114, 0.5, v114
	v_mul_f32_e32 v115, 0.5, v115
	v_fma_f32 v192, v2, v112, v192
	v_fma_f32 v193, v3, v113, v193
	v_fma_f32 v194, v4, v114, v194
	v_fma_f32 v195, v5, v115, v195
	global_store_dwordx4 v163, v[192:195], s[48:49] offset:192
	s_add_i32 s7, s7, s84
	s_cmpk_gt_i32 s7, 0xff
	s_cbranch_scc0 .LBB0_434

.LBB0_466:
	s_or_b64 exec, exec, s[0:1]
	v_cmp_eq_u32_e32 vcc, 0x1600, v11
	s_nop 1
	v_cndmask_b32_e64 v166, 0, 1, vcc
	v_cmp_eq_u32_e32 vcc, 0xb00, v4
	s_nop 1
	v_cndmask_b32_e64 v166, v166, 1, vcc
	v_lshlrev_b32_e32 v173, 5, v4
	v_mul_i32_i24_e32 v14, v4, v10
	v_mad_u64_u32 v[14:15], s[0:1], v14, v11, 0
	v_mul_hi_i32_i24_e32 v13, v4, v10
	v_mov_b32_e32 v38, v15
	v_mad_u64_u32 v[38:39], s[0:1], v13, v11, v[38:39]
	v_mov_b32_e32 v15, v38
	v_lshl_add_u64 v[6:7], v[14:15], 2, v[6:7]
	v_lshlrev_b32_sdwa v14, v159, sext(v9) dst_sel:DWORD dst_unused:UNUSED_PAD src0_sel:DWORD src1_sel:WORD_0
	v_bfe_u32 v13, v5, 4, 4
	v_ashrrev_i32_e32 v9, 31, v8
	v_or_b32_e32 v15, v13, v14
	v_lshl_add_u64 v[46:47], v[8:9], 2, v[6:7]
	v_or_b32_e32 v8, 16, v15
	v_mul_hi_i32_i24_e32 v7, v15, v11
	v_mul_i32_i24_e32 v6, v15, v11
	v_mul_hi_i32_i24_e32 v9, v8, v11
	v_mul_i32_i24_e32 v8, v8, v11
	v_lshl_add_u64 v[6:7], v[6:7], 2, v[46:47]
	v_lshl_add_u64 v[38:39], v[8:9], 2, v[46:47]
	s_waitcnt vmcnt(0)
	s_barrier
	global_load_dwordx4 v[6:9], v[6:7], off nt
	s_nop 0
	global_load_dwordx4 v[38:41], v[38:39], off nt
	v_or_b32_e32 v37, 32, v15
	v_mul_hi_i32_i24_e32 v43, v37, v11
	v_mul_i32_i24_e32 v42, v37, v11
	v_lshl_add_u64 v[42:43], v[42:43], 2, v[46:47]
	v_or_b32_e32 v15, 48, v15
	global_load_dwordx4 v[42:45], v[42:43], off nt
	v_mul_hi_i32_i24_e32 v49, v15, v11
	v_mul_i32_i24_e32 v48, v15, v11
	v_lshl_add_u64 v[46:47], v[48:49], 2, v[46:47]
	global_load_dwordx4 v[46:49], v[46:47], off nt
	v_readlane_b32 s0, v217, 7
	v_readlane_b32 s1, v217, 8
	v_lshrrev_b32_e32 v15, 8, v5
	v_bfe_u32 v37, v5, 2, 6
	v_mov_b64_e32 v[50:51], s[0:1]
	s_mov_b32 s0, 0x3500000
	v_mad_i64_i32 v[10:11], s[0:1], v10, s0, v[50:51]
	v_lshlrev_b32_e32 v52, 4, v5
	s_movk_i32 s0, 0x4100
	v_lshlrev_b32_e32 v12, 2, v12
	v_and_b32_e32 v53, 0xfc, v5
	v_mad_i32_i24 v50, v15, s0, 0
	v_mul_u32_u24_e32 v5, 0x104, v13
	v_and_b32_e32 v13, 48, v52
	v_or_b32_e32 v0, v37, v0
	v_mov_b32_e32 v169, v0
	v_lshl_add_u64 v[2:3], v[2:3], 1, v[10:11]
	v_mov_b32_e32 v167, v2
	v_mov_b32_e32 v168, v3
	v_add3_u32 v12, v50, v12, v5
	v_mul_u32_u24_e32 v10, 0x104, v13
	v_mul_hi_i32_i24_e32 v5, v4, v0
	v_mul_i32_i24_e32 v4, v4, v0
	v_ashrrev_i32_e32 v15, 31, v14
	v_lshlrev_b32_e32 v0, 1, v13
	v_add_u32_e32 v13, 0x1040, v12
	v_add3_u32 v50, v50, v10, v53
	v_lshl_add_u64 v[2:3], v[4:5], 1, v[2:3]
	v_add_u32_e32 v37, 0x1048, v12
	v_add_u32_e32 v51, 0x2080, v12
	v_add_u32_e32 v52, 0x2088, v12
	v_add_u32_e32 v54, 0x30c0, v12
	v_add_u32_e32 v55, 0x30c8, v12
	v_add_u32_e32 v53, 0x400, v50
	v_add_u32_e32 v56, 0x800, v50
	v_add_u32_e32 v57, 0xc00, v50
	v_lshl_add_u64 v[10:11], v[14:15], 1, v[2:3]
	v_lshl_add_u64 v[10:11], v[10:11], 0, v[0:1]
	v_lshlrev_b32_e32 v170, 1, v14
	v_add_u32_e32 v170, v170, v0
	v_lshrrev_b32_e32 v171, 4, v169
	v_mul_lo_u32 v171, v171, v173
	v_and_b32_e32 v172, 15, v169
	v_lshl_add_u32 v171, v172, 6, v171
	v_lshrrev_b32_e32 v172, 6, v170
	v_lshl_add_u32 v171, v172, 10, v171
	v_and_b32_e32 v172, 63, v170
	v_add_u32_e32 v171, v171, v172
	v_add_co_u32_e32 v167, vcc, v167, v171
	s_nop 1
	v_addc_co_u32_e32 v168, vcc, 0, v168, vcc
	v_cmp_eq_u32_e32 vcc, 1, v166
	s_nop 1
	v_cndmask_b32_e32 v10, v10, v167, vcc
	v_cndmask_b32_e32 v11, v11, v168, vcc
	s_waitcnt vmcnt(3)
	ds_write2_b32 v12, v6, v7 offset1:1
	ds_write2_b32 v12, v8, v9 offset0:2 offset1:3
	s_waitcnt vmcnt(2)
	ds_write2_b32 v13, v38, v39 offset1:1
	ds_write2_b32 v37, v40, v41 offset1:1
	s_waitcnt vmcnt(1)
	ds_write2_b32 v51, v42, v43 offset1:1
	ds_write2_b32 v52, v44, v45 offset1:1
	s_waitcnt vmcnt(0)
	ds_write2_b32 v54, v46, v47 offset1:1
	ds_write2_b32 v55, v48, v49 offset1:1
	s_waitcnt lgkmcnt(0)
	s_barrier
	ds_read2_b32 v[2:3], v50 offset1:65
	ds_read2_b32 v[4:5], v50 offset0:130 offset1:195
	ds_read2_b32 v[6:7], v53 offset0:4 offset1:69
	ds_read2_b32 v[8:9], v53 offset0:134 offset1:199
	ds_read2_b32 v[12:13], v56 offset0:8 offset1:73
	ds_read2_b32 v[14:15], v56 offset0:138 offset1:203
	ds_read2_b32 v[38:39], v57 offset0:12 offset1:77
	ds_read2_b32 v[40:41], v57 offset0:142 offset1:207
	s_waitcnt lgkmcnt(7)
	v_cvt_pk_bf16_f32 v2, v2, v3
	s_waitcnt lgkmcnt(6)
	v_cvt_pk_bf16_f32 v3, v4, v5
	s_waitcnt lgkmcnt(5)
	v_cvt_pk_bf16_f32 v4, v6, v7
	s_waitcnt lgkmcnt(4)
	v_cvt_pk_bf16_f32 v5, v8, v9
	s_waitcnt lgkmcnt(3)
	v_cvt_pk_bf16_f32 v6, v12, v13
	s_waitcnt lgkmcnt(2)
	v_cvt_pk_bf16_f32 v7, v14, v15
	s_waitcnt lgkmcnt(1)
	v_cvt_pk_bf16_f32 v8, v38, v39
	s_waitcnt lgkmcnt(0)
	v_cvt_pk_bf16_f32 v9, v40, v41
	global_store_dwordx4 v[10:11], v[2:5], off
	global_store_dwordx4 v[10:11], v[6:9], off offset:16
